# up-proj fast epilogue: conv/bias coefficients staged to LDS by DMA in the tile prologue (no VMEM wait behind the next-tile prefetch)
# speedup vs baseline: 1.0186x; 1.0046x over previous
; #define PG8_BAR __builtin_amdgcn_s_barrier()
; template <class Epi, int OVL>
; DI void gemm_phase(LAS unsigned char* lds, const Gemm g, const Sched& S, const Epi& E) {
;     ...
; #pragma unroll
;         for (int a = 0; a < 2; ++a)
; #pragma unroll
;             for (int b = 0; b < 2; ++b)
; #pragma unroll
;                 for (int m = 0; m < 4; ++m)
; #pragma unroll
;                     for (int n = 0; n < 2; ++n) acc[a][b][m][n] = (f32x4){0.f, 0.f, 0.f, 0.f};
;         cur = nxt; cA = nA; cB = nB; ++ui;
;         if (wr == 1) PG8_BAR;
;     DI void operator()(const f32x4 (&acc)[2][2][4][2], const Unit& u, int wr, int wc, int fr_, int fq_) const {
;     ...
;             const int sv = cv0 + 4 * n, sg = FF + cv0 + 4 * n;
;             const f32x4 vp = *(const f32x4*)(cw + sv), vm = *(const f32x4*)(cw + NUP + sv), vn = *(const f32x4*)(cw + 2 * NUP + sv), vb = *(const f32x4*)(cb + sv);
;             const f32x4 gp = *(const f32x4*)(cw + sg), gm = *(const f32x4*)(cw + NUP + sg), gn = *(const f32x4*)(cw + 2 * NUP + sg), gb = *(const f32x4*)(cb + sg);
.LBB0_1264:
	s_ashr_i32 s93, s92, 31
	s_lshl_b64 s[14:15], s[92:93], 19
	v_readlane_b32 s5, v255, 24
	s_add_u32 s96, s5, s14
	v_readlane_b32 s5, v255, 27
	s_addc_u32 s97, s5, s15
	s_and_b64 s[8:9], s[8:9], exec
	s_cselect_b32 s5, s97, s11
	s_cselect_b32 s14, s96, s10
	s_add_u32 s8, s12, 0x3e080
	s_addc_u32 s9, s13, 0
	s_add_u32 s15, s10, 0x100
	v_mov_b32_e32 v0, 0
	s_addc_u32 s17, s11, 0
	s_mov_b32 s18, -2
	v_mov_b32_e32 v1, v0
	v_mov_b32_e32 v2, v0
	v_mov_b32_e32 v3, v0
	v_mov_b32_e32 v64, v0
	v_mov_b32_e32 v65, v0
	v_mov_b32_e32 v66, v0
	v_mov_b32_e32 v67, v0
	v_mov_b32_e32 v8, v0
	v_mov_b32_e32 v9, v0
	v_mov_b32_e32 v10, v0
	v_mov_b32_e32 v11, v0
	v_mov_b32_e32 v72, v0
	v_mov_b32_e32 v73, v0
	v_mov_b32_e32 v74, v0
	v_mov_b32_e32 v75, v0
	v_mov_b32_e32 v16, v0
	v_mov_b32_e32 v17, v0
	v_mov_b32_e32 v18, v0
	v_mov_b32_e32 v19, v0
	v_mov_b32_e32 v80, v0
	v_mov_b32_e32 v81, v0
	v_mov_b32_e32 v82, v0
	v_mov_b32_e32 v83, v0
	v_mov_b32_e32 v24, v0
	v_mov_b32_e32 v25, v0
	v_mov_b32_e32 v26, v0
	v_mov_b32_e32 v27, v0
	s_waitcnt vmcnt(0)
	v_mov_b32_e32 v88, v0
	v_mov_b32_e32 v89, v0
	v_mov_b32_e32 v90, v0
	v_mov_b32_e32 v91, v0
	v_mov_b32_e32 v4, v0
	v_mov_b32_e32 v5, v0
	v_mov_b32_e32 v6, v0
	v_mov_b32_e32 v7, v0
	v_mov_b32_e32 v68, v0
	v_mov_b32_e32 v69, v0
	v_mov_b32_e32 v70, v0
	v_mov_b32_e32 v71, v0
	v_mov_b32_e32 v12, v0
	v_mov_b32_e32 v13, v0
	v_mov_b32_e32 v14, v0
	v_mov_b32_e32 v15, v0
	v_mov_b32_e32 v76, v0
	v_mov_b32_e32 v77, v0
	v_mov_b32_e32 v78, v0
	v_mov_b32_e32 v79, v0
	v_mov_b32_e32 v20, v0
	v_mov_b32_e32 v21, v0
	v_mov_b32_e32 v22, v0
	v_mov_b32_e32 v23, v0
	v_mov_b32_e32 v84, v0
	v_mov_b32_e32 v85, v0
	v_mov_b32_e32 v86, v0
	v_mov_b32_e32 v87, v0
	v_mov_b32_e32 v28, v0
	v_mov_b32_e32 v29, v0
	v_mov_b32_e32 v30, v0
	v_mov_b32_e32 v31, v0
	v_mov_b32_e32 v92, v0
	v_mov_b32_e32 v93, v0
	v_mov_b32_e32 v94, v0
	v_mov_b32_e32 v95, v0
	v_mov_b32_e32 v32, v0
	v_mov_b32_e32 v33, v0
	v_mov_b32_e32 v34, v0
	v_mov_b32_e32 v35, v0
	v_mov_b32_e32 v128, v0
	v_mov_b32_e32 v129, v0
	v_mov_b32_e32 v130, v0
	v_mov_b32_e32 v131, v0
	v_mov_b32_e32 v40, v0
	v_mov_b32_e32 v41, v0
	v_mov_b32_e32 v42, v0
	v_mov_b32_e32 v43, v0
	v_mov_b32_e32 v136, v0
	v_mov_b32_e32 v137, v0
	v_mov_b32_e32 v138, v0
	v_mov_b32_e32 v139, v0
	v_mov_b32_e32 v48, v0
	v_mov_b32_e32 v49, v0
	v_mov_b32_e32 v50, v0
	v_mov_b32_e32 v51, v0
	v_mov_b32_e32 v144, v0
	v_mov_b32_e32 v145, v0
	v_mov_b32_e32 v146, v0
	v_mov_b32_e32 v147, v0
	v_mov_b32_e32 v56, v0
	v_mov_b32_e32 v57, v0
	v_mov_b32_e32 v58, v0
	v_mov_b32_e32 v59, v0
	v_mov_b32_e32 v152, v0
	v_mov_b32_e32 v153, v0
	v_mov_b32_e32 v154, v0
	v_mov_b32_e32 v155, v0
	v_mov_b32_e32 v36, v0
	v_mov_b32_e32 v37, v0
	v_mov_b32_e32 v38, v0
	v_mov_b32_e32 v39, v0
	v_mov_b32_e32 v132, v0
	v_mov_b32_e32 v133, v0
	v_mov_b32_e32 v134, v0
	v_mov_b32_e32 v135, v0
	v_mov_b32_e32 v44, v0
	v_mov_b32_e32 v45, v0
	v_mov_b32_e32 v46, v0
	v_mov_b32_e32 v47, v0
	v_mov_b32_e32 v140, v0
	v_mov_b32_e32 v141, v0
	v_mov_b32_e32 v142, v0
	v_mov_b32_e32 v143, v0
	v_mov_b32_e32 v52, v0
	v_mov_b32_e32 v53, v0
	v_mov_b32_e32 v54, v0
	v_mov_b32_e32 v55, v0
	v_mov_b32_e32 v148, v0
	v_mov_b32_e32 v149, v0
	v_mov_b32_e32 v150, v0
	v_mov_b32_e32 v151, v0
	v_mov_b32_e32 v60, v0
	v_mov_b32_e32 v61, v0
	v_mov_b32_e32 v62, v0
	v_mov_b32_e32 v63, v0
	v_mov_b32_e32 v156, v0
	v_mov_b32_e32 v157, v0
	v_mov_b32_e32 v158, v0
	v_mov_b32_e32 v159, v0
	s_and_b32 s100, s58, 1
	s_lshl_b32 s100, s100, 12
	s_add_i32 s100, s100, 0x20000
	v_readlane_b32 s98, v255, 14
	v_readlane_b32 s99, v255, 15
	v_readlane_b32 s28, v255, 16
	v_readlane_b32 s29, v255, 17
	s_lshl_b32 s101, s4, 9
	v_and_b32_e32 v96, 63, v199
	v_and_b32_e32 v97, 31, v96
	v_cmp_lt_u32_e64 s[26:27], 31, v96
	v_lshlrev_b32_e32 v97, 4, v97
	s_add_u32 s98, s98, s101
	s_addc_u32 s99, s99, 0
	s_add_u32 s28, s28, s101
	s_addc_u32 s29, s29, 0
	v_mov_b32_e32 v98, 0x5800
	v_mov_b32_e32 v99, 0x2c00
	v_mov_b32_e32 v100, 0xb000
	v_mov_b32_e32 v102, 0x8400
	v_mov_b32_e32 v101, 0xdc00
	v_cndmask_b32_e64 v98, 0, v98, s[26:27]
	v_cndmask_b32_e64 v100, v100, v99, s[26:27]
	v_cndmask_b32_e64 v102, v102, v101, s[26:27]
	v_cndmask_b32_e64 v99, 0, v99, s[26:27]
	v_add_u32_e32 v98, v97, v98
	v_add_u32_e32 v100, v97, v100
	v_add_u32_e32 v102, v97, v102
	v_add_u32_e32 v99, v97, v99
	s_mov_b32 m0, s100
	s_nop 0
	global_load_lds_dwordx4 v98, s[98:99]
	s_add_i32 m0, s100, 0x400
	s_nop 0
	global_load_lds_dwordx4 v100, s[98:99]
	s_add_i32 m0, s100, 0x800
	s_nop 0
	global_load_lds_dwordx4 v102, s[98:99]
	s_add_i32 m0, s100, 0xc00
	s_nop 0
	global_load_lds_dwordx4 v99, s[28:29]

;     DI void operator()(const f32x4 (&acc)[2][2][4][2], const Unit& u, int wr, int wc, int fr_, int fq_) const {
;         int fr = fr_, fq = fq_; asm volatile("" : "+v"(fr), "+v"(fq));
;         const int lane = fr | (fq << 4);
;         const int src_up = (lane & 48) | ((fr + 15) & 15), src_dn = (lane & 48) | ((fr + 1) & 15);
;         const int cv0 = u.pn * 128 + wc * 32 + 8 * fq;
; #pragma unroll
;         for (int n = 0; n < 2; ++n) {
;             const int sv = cv0 + 4 * n, sg = FF + cv0 + 4 * n;
;             const f32x4 vp = *(const f32x4*)(cw + sv), vm = *(const f32x4*)(cw + NUP + sv), vn = *(const f32x4*)(cw + 2 * NUP + sv), vb = *(const f32x4*)(cb + sv);
;             const f32x4 gp = *(const f32x4*)(cw + sg), gm = *(const f32x4*)(cw + NUP + sg), gn = *(const f32x4*)(cw + 2 * NUP + sg), gb = *(const f32x4*)(cb + sg);
; #pragma unroll
;             for (int ai = 0; ai < 2; ++ai) {
;                 const int tok0 = u.pm * 248 + (2 * ai + wr) * 62 - 1;
; #pragma unroll
;                 for (int m = 0; m < 4; ++m) { f32x4 zv, zg;
;                     CONV_ONE(acc, ai, 0, n, m, zv, vp, vm, vn); CONV_ONE(acc, ai, 1, n, m, zg, gp, gm, gn);
;                     zv = zv + vb; zg = zg + gb;
.LBB0_1268:
	s_mul_i32 s98, s16, 0xf8
	s_add_i32 s99, s98, -1
	s_add_i32 s100, s98, 0xf8
	s_ashr_i32 s99, s99, 12
	s_ashr_i32 s100, s100, 12
	s_cmp_lg_u32 s99, s100
	s_cbranch_scc1 .Lup_slow
	s_mov_b64 s[28:29], exec
	v_readlane_b32 s9, v255, 18
	v_readlane_b32 s22, v255, 22
	s_lshl_b32 s8, s4, 7
	v_cmp_eq_u32_e64 s[10:11], 0, v180
	v_cmp_eq_u32_e64 s[12:13], 15, v180
	v_cmp_ne_u32_e64 s[14:15], 0, v180
	v_cmp_ne_u32_e64 s[24:25], 15, v180
	s_or_b32 s8, s8, s9
	s_add_i32 s22, s22, s98
	v_lshl_add_u32 v170, v181, 3, s8
	v_add_u32_e32 v186, s22, v180
	s_and_b32 s100, s58, 1
	s_lshl_b32 s100, s100, 12
	s_lshl_b32 s18, s9, 2
	s_add_i32 s100, s100, 0x20000
	s_add_i32 s100, s100, s18
	v_lshl_add_u32 v188, v181, 5, s100
	v_add_u32_e32 v186, -1, v186
	v_mul_u32_u24_e32 v186, 0x1600, v186
	v_lshl_add_u32 v186, v170, 1, v186
	v_mov_b32_e32 v187, 0
	s_mov_b32 s27, 0
	s_mov_b32 s40, 0x3d372713
	s_mov_b32 s42, 0xc0135761
	s_mov_b32 s44, 1.0
	v_lshl_add_u64 v[186:187], v[186:187], 0, s[84:85]
	ds_read_b128 v[96:99], v188 offset:0
	ds_read_b128 v[100:103], v188 offset:512
	ds_read_b128 v[104:107], v188 offset:1024
	ds_read_b128 v[108:111], v188 offset:3072
	ds_read_b128 v[112:115], v188 offset:1536
	ds_read_b128 v[116:119], v188 offset:2048
	ds_read_b128 v[120:123], v188 offset:2560
	ds_read_b128 v[124:127], v188 offset:3584
	s_waitcnt lgkmcnt(0)
	v_cndmask_b32_e64 v200, 0, v96, s[10:11]
	v_cndmask_b32_e64 v204, 0, v104, s[12:13]
	v_cndmask_b32_e64 v208, 0, v112, s[10:11]
	v_cndmask_b32_e64 v212, 0, v120, s[12:13]
	v_cndmask_b32_e64 v201, 0, v97, s[10:11]
	v_cndmask_b32_e64 v205, 0, v105, s[12:13]
	v_cndmask_b32_e64 v209, 0, v113, s[10:11]
	v_cndmask_b32_e64 v213, 0, v121, s[12:13]
	v_cndmask_b32_e64 v202, 0, v98, s[10:11]
	v_cndmask_b32_e64 v206, 0, v106, s[12:13]
	v_cndmask_b32_e64 v210, 0, v114, s[10:11]
	v_cndmask_b32_e64 v214, 0, v122, s[12:13]
	v_cndmask_b32_e64 v203, 0, v99, s[10:11]
	v_cndmask_b32_e64 v207, 0, v107, s[12:13]
	v_cndmask_b32_e64 v211, 0, v115, s[10:11]
	v_cndmask_b32_e64 v215, 0, v123, s[12:13]
	v_pk_fma_f32 v[216:217], v[156:157], v[100:101], v[108:109]
	v_pk_fma_f32 v[218:219], v[148:149], v[100:101], v[108:109]
	v_pk_fma_f32 v[220:221], v[158:159], v[102:103], v[110:111]
	v_pk_fma_f32 v[222:223], v[150:151], v[102:103], v[110:111]
	v_pk_fma_f32 v[224:225], v[152:153], v[116:117], v[124:125]
	v_pk_fma_f32 v[226:227], v[144:145], v[116:117], v[124:125]
	v_pk_fma_f32 v[228:229], v[154:155], v[118:119], v[126:127]
	v_pk_fma_f32 v[194:195], v[146:147], v[118:119], v[126:127]
	v_fmac_f32_dpp v216, v156, v96 row_shr:1 row_mask:0xf bank_mask:0xf
	v_fmac_f32_dpp v218, v148, v96 row_shr:1 row_mask:0xf bank_mask:0xf
	v_fmac_f32_dpp v220, v158, v98 row_shr:1 row_mask:0xf bank_mask:0xf
	v_fmac_f32_dpp v222, v150, v98 row_shr:1 row_mask:0xf bank_mask:0xf
	v_fmac_f32_dpp v224, v152, v112 row_shr:1 row_mask:0xf bank_mask:0xf
	v_fmac_f32_dpp v226, v144, v112 row_shr:1 row_mask:0xf bank_mask:0xf
	v_fmac_f32_dpp v228, v154, v114 row_shr:1 row_mask:0xf bank_mask:0xf
	v_fmac_f32_dpp v194, v146, v114 row_shr:1 row_mask:0xf bank_mask:0xf
	v_fmac_f32_dpp v216, v156, v104 row_shl:1 row_mask:0xf bank_mask:0xf
	v_fmac_f32_dpp v218, v148, v104 row_shl:1 row_mask:0xf bank_mask:0xf
	v_fmac_f32_dpp v220, v158, v106 row_shl:1 row_mask:0xf bank_mask:0xf
	v_fmac_f32_dpp v222, v150, v106 row_shl:1 row_mask:0xf bank_mask:0xf
	v_fmac_f32_dpp v224, v152, v120 row_shl:1 row_mask:0xf bank_mask:0xf
	v_fmac_f32_dpp v226, v144, v120 row_shl:1 row_mask:0xf bank_mask:0xf
	v_fmac_f32_dpp v228, v154, v122 row_shl:1 row_mask:0xf bank_mask:0xf
	v_fmac_f32_dpp v194, v146, v122 row_shl:1 row_mask:0xf bank_mask:0xf
	v_fmac_f32_dpp v216, v148, v204 row_ror:15 row_mask:0xf bank_mask:0xf
	v_fmac_f32_dpp v218, v156, v200 row_ror:1 row_mask:0xf bank_mask:0xf
	v_fmac_f32_dpp v220, v150, v206 row_ror:15 row_mask:0xf bank_mask:0xf
	v_fmac_f32_dpp v222, v158, v202 row_ror:1 row_mask:0xf bank_mask:0xf
	v_fmac_f32_dpp v224, v144, v212 row_ror:15 row_mask:0xf bank_mask:0xf
	v_fmac_f32_dpp v226, v152, v208 row_ror:1 row_mask:0xf bank_mask:0xf
	v_fmac_f32_dpp v228, v146, v214 row_ror:15 row_mask:0xf bank_mask:0xf
	v_fmac_f32_dpp v194, v154, v210 row_ror:1 row_mask:0xf bank_mask:0xf
	v_fmac_f32_dpp v217, v157, v97 row_shr:1 row_mask:0xf bank_mask:0xf
	v_fmac_f32_dpp v218, v140, v204 row_ror:15 row_mask:0xf bank_mask:0xf
	v_fmac_f32_dpp v221, v159, v99 row_shr:1 row_mask:0xf bank_mask:0xf
	v_fmac_f32_dpp v222, v142, v206 row_ror:15 row_mask:0xf bank_mask:0xf
	v_fmac_f32_dpp v225, v153, v113 row_shr:1 row_mask:0xf bank_mask:0xf
	v_fmac_f32_dpp v226, v136, v212 row_ror:15 row_mask:0xf bank_mask:0xf
	v_fmac_f32_dpp v229, v155, v115 row_shr:1 row_mask:0xf bank_mask:0xf
	v_fmac_f32_dpp v194, v138, v214 row_ror:15 row_mask:0xf bank_mask:0xf
	v_fmac_f32_dpp v217, v157, v105 row_shl:1 row_mask:0xf bank_mask:0xf
	v_fmac_f32_dpp v219, v149, v97 row_shr:1 row_mask:0xf bank_mask:0xf
	v_fmac_f32_dpp v221, v159, v107 row_shl:1 row_mask:0xf bank_mask:0xf
	v_fmac_f32_dpp v223, v151, v99 row_shr:1 row_mask:0xf bank_mask:0xf
	v_fmac_f32_dpp v225, v153, v121 row_shl:1 row_mask:0xf bank_mask:0xf
	v_fmac_f32_dpp v227, v145, v113 row_shr:1 row_mask:0xf bank_mask:0xf
	v_fmac_f32_dpp v229, v155, v123 row_shl:1 row_mask:0xf bank_mask:0xf
	v_fmac_f32_dpp v195, v147, v115 row_shr:1 row_mask:0xf bank_mask:0xf
	v_fmac_f32_dpp v217, v149, v205 row_ror:15 row_mask:0xf bank_mask:0xf
	v_fmac_f32_dpp v219, v149, v105 row_shl:1 row_mask:0xf bank_mask:0xf
	v_fmac_f32_dpp v221, v151, v207 row_ror:15 row_mask:0xf bank_mask:0xf
	v_fmac_f32_dpp v223, v151, v107 row_shl:1 row_mask:0xf bank_mask:0xf
;     DI void operator()(const f32x4 (&acc)[2][2][4][2], const Unit& u, int wr, int wc, int fr_, int fq_) const {
;     ...
;                     for (int e = 0; e < 4; ++e) { const float x = zg[e]; const float uu = 1.5957691216f * (x + 0.044715f * x * x * x);
;                         ov[e] = zv[e] * x * __builtin_amdgcn_rcpf(1.f + __expf(-uu)); }
	v_fmac_f32_dpp v225, v145, v213 row_ror:15 row_mask:0xf bank_mask:0xf
	v_fmac_f32_dpp v227, v145, v121 row_shl:1 row_mask:0xf bank_mask:0xf
	v_fmac_f32_dpp v229, v147, v215 row_ror:15 row_mask:0xf bank_mask:0xf
	v_fmac_f32_dpp v195, v147, v123 row_shl:1 row_mask:0xf bank_mask:0xf
	v_fmac_f32_dpp v219, v157, v201 row_ror:1 row_mask:0xf bank_mask:0xf
	v_fmac_f32_dpp v223, v159, v203 row_ror:1 row_mask:0xf bank_mask:0xf
	v_fmac_f32_dpp v227, v153, v209 row_ror:1 row_mask:0xf bank_mask:0xf
	v_fmac_f32_dpp v195, v155, v211 row_ror:1 row_mask:0xf bank_mask:0xf
	v_fmac_f32_dpp v219, v141, v205 row_ror:15 row_mask:0xf bank_mask:0xf
	v_fmac_f32_dpp v223, v143, v207 row_ror:15 row_mask:0xf bank_mask:0xf
	v_fmac_f32_dpp v227, v137, v213 row_ror:15 row_mask:0xf bank_mask:0xf
	v_fmac_f32_dpp v195, v139, v215 row_ror:15 row_mask:0xf bank_mask:0xf
	v_pk_fma_f32 v[156:157], v[140:141], v[100:101], v[108:109]
	v_pk_fma_f32 v[158:159], v[142:143], v[102:103], v[110:111]
	v_pk_fma_f32 v[152:153], v[136:137], v[116:117], v[124:125]
	v_pk_fma_f32 v[154:155], v[138:139], v[118:119], v[126:127]
	v_fmac_f32_dpp v156, v140, v96 row_shr:1 row_mask:0xf bank_mask:0xf
	v_fmac_f32_dpp v158, v142, v98 row_shr:1 row_mask:0xf bank_mask:0xf
	v_fmac_f32_dpp v152, v136, v112 row_shr:1 row_mask:0xf bank_mask:0xf
	v_fmac_f32_dpp v154, v138, v114 row_shr:1 row_mask:0xf bank_mask:0xf
	v_fmac_f32_dpp v156, v140, v104 row_shl:1 row_mask:0xf bank_mask:0xf
	v_fmac_f32_dpp v158, v142, v106 row_shl:1 row_mask:0xf bank_mask:0xf
	v_fmac_f32_dpp v152, v136, v120 row_shl:1 row_mask:0xf bank_mask:0xf
	v_fmac_f32_dpp v154, v138, v122 row_shl:1 row_mask:0xf bank_mask:0xf
	v_fmac_f32_dpp v156, v148, v200 row_ror:1 row_mask:0xf bank_mask:0xf
	v_fmac_f32_dpp v158, v150, v202 row_ror:1 row_mask:0xf bank_mask:0xf
	v_fmac_f32_dpp v152, v144, v208 row_ror:1 row_mask:0xf bank_mask:0xf
	v_fmac_f32_dpp v154, v146, v210 row_ror:1 row_mask:0xf bank_mask:0xf
	v_fmac_f32_dpp v156, v132, v204 row_ror:15 row_mask:0xf bank_mask:0xf
	v_fmac_f32_dpp v158, v134, v206 row_ror:15 row_mask:0xf bank_mask:0xf
	v_fmac_f32_dpp v152, v128, v212 row_ror:15 row_mask:0xf bank_mask:0xf
	v_fmac_f32_dpp v154, v130, v214 row_ror:15 row_mask:0xf bank_mask:0xf
	v_fmac_f32_dpp v157, v141, v97 row_shr:1 row_mask:0xf bank_mask:0xf
	v_fmac_f32_dpp v159, v143, v99 row_shr:1 row_mask:0xf bank_mask:0xf
	v_fmac_f32_dpp v153, v137, v113 row_shr:1 row_mask:0xf bank_mask:0xf
	v_fmac_f32_dpp v155, v139, v115 row_shr:1 row_mask:0xf bank_mask:0xf
	v_fmac_f32_dpp v157, v141, v105 row_shl:1 row_mask:0xf bank_mask:0xf
	v_fmac_f32_dpp v159, v143, v107 row_shl:1 row_mask:0xf bank_mask:0xf
	v_fmac_f32_dpp v153, v137, v121 row_shl:1 row_mask:0xf bank_mask:0xf
	v_fmac_f32_dpp v155, v139, v123 row_shl:1 row_mask:0xf bank_mask:0xf
	v_fmac_f32_dpp v157, v149, v201 row_ror:1 row_mask:0xf bank_mask:0xf
	v_fmac_f32_dpp v159, v151, v203 row_ror:1 row_mask:0xf bank_mask:0xf
	v_fmac_f32_dpp v153, v145, v209 row_ror:1 row_mask:0xf bank_mask:0xf
	v_fmac_f32_dpp v155, v147, v211 row_ror:1 row_mask:0xf bank_mask:0xf
	v_fmac_f32_dpp v157, v133, v205 row_ror:15 row_mask:0xf bank_mask:0xf
	v_fmac_f32_dpp v159, v135, v207 row_ror:15 row_mask:0xf bank_mask:0xf
	v_fmac_f32_dpp v153, v129, v213 row_ror:15 row_mask:0xf bank_mask:0xf
	v_fmac_f32_dpp v155, v131, v215 row_ror:15 row_mask:0xf bank_mask:0xf
	v_pk_fma_f32 v[148:149], v[132:133], v[100:101], v[108:109]
	v_pk_fma_f32 v[150:151], v[134:135], v[102:103], v[110:111]
	v_pk_fma_f32 v[144:145], v[128:129], v[116:117], v[124:125]
	v_pk_fma_f32 v[146:147], v[130:131], v[118:119], v[126:127]
	v_fmac_f32_dpp v148, v132, v96 row_shr:1 row_mask:0xf bank_mask:0xf
	v_fmac_f32_dpp v150, v134, v98 row_shr:1 row_mask:0xf bank_mask:0xf
	v_fmac_f32_dpp v144, v128, v112 row_shr:1 row_mask:0xf bank_mask:0xf
	v_fmac_f32_dpp v146, v130, v114 row_shr:1 row_mask:0xf bank_mask:0xf
	v_fmac_f32_dpp v148, v132, v104 row_shl:1 row_mask:0xf bank_mask:0xf
	v_fmac_f32_dpp v150, v134, v106 row_shl:1 row_mask:0xf bank_mask:0xf
	v_fmac_f32_dpp v144, v128, v120 row_shl:1 row_mask:0xf bank_mask:0xf
	v_fmac_f32_dpp v146, v130, v122 row_shl:1 row_mask:0xf bank_mask:0xf
	v_fmac_f32_dpp v148, v140, v200 row_ror:1 row_mask:0xf bank_mask:0xf
	v_fmac_f32_dpp v150, v142, v202 row_ror:1 row_mask:0xf bank_mask:0xf
	v_fmac_f32_dpp v144, v136, v208 row_ror:1 row_mask:0xf bank_mask:0xf
	v_fmac_f32_dpp v146, v138, v210 row_ror:1 row_mask:0xf bank_mask:0xf
	v_fmac_f32_dpp v149, v133, v97 row_shr:1 row_mask:0xf bank_mask:0xf
	v_fmac_f32_dpp v151, v135, v99 row_shr:1 row_mask:0xf bank_mask:0xf
	v_fmac_f32_dpp v145, v129, v113 row_shr:1 row_mask:0xf bank_mask:0xf
	v_fmac_f32_dpp v147, v131, v115 row_shr:1 row_mask:0xf bank_mask:0xf
	v_fmac_f32_dpp v149, v133, v105 row_shl:1 row_mask:0xf bank_mask:0xf
	v_fmac_f32_dpp v151, v135, v107 row_shl:1 row_mask:0xf bank_mask:0xf
	v_fmac_f32_dpp v145, v129, v121 row_shl:1 row_mask:0xf bank_mask:0xf
	v_fmac_f32_dpp v147, v131, v123 row_shl:1 row_mask:0xf bank_mask:0xf
	v_fmac_f32_dpp v149, v141, v201 row_ror:1 row_mask:0xf bank_mask:0xf
	v_fmac_f32_dpp v151, v143, v203 row_ror:1 row_mask:0xf bank_mask:0xf
	v_fmac_f32_dpp v145, v137, v209 row_ror:1 row_mask:0xf bank_mask:0xf
	v_fmac_f32_dpp v147, v139, v211 row_ror:1 row_mask:0xf bank_mask:0xf
	v_pk_mul_f32 v[172:173], v[224:225], s[40:41] op_sel_hi:[1,0]
	v_pk_mul_f32 v[174:175], v[228:229], s[40:41] op_sel_hi:[1,0]
	v_pk_mul_f32 v[172:173], v[224:225], v[172:173]
	v_pk_mul_f32 v[174:175], v[228:229], v[174:175]
	v_pk_fma_f32 v[172:173], v[224:225], v[172:173], v[224:225]
	v_pk_fma_f32 v[174:175], v[228:229], v[174:175], v[228:229]
	v_pk_mul_f32 v[172:173], v[172:173], s[42:43] op_sel_hi:[1,0]
; DI unsigned cvtpk(float lo, float hi) { unsigned r; asm volatile("v_cvt_pk_bf16_f32 %0, %1, %2" : "=v"(r) : "v"(lo), "v"(hi)); return r; }
;     DI void operator()(const f32x4 (&acc)[2][2][4][2], const Unit& u, int wr, int wc, int fr_, int fq_) const {
;     ...
;                 for (int m = 0; m < 4; ++m) { f32x4 zv, zg;
;                     CONV_ONE(acc, ai, 0, n, m, zv, vp, vm, vn); CONV_ONE(acc, ai, 1, n, m, zg, gp, gm, gn);
;                     zv = zv + vb; zg = zg + gb;
;                     float ov[4];
; #pragma unroll
;                     for (int e = 0; e < 4; ++e) { const float x = zg[e]; const float uu = 1.5957691216f * (x + 0.044715f * x * x * x);
;                         ov[e] = zv[e] * x * __builtin_amdgcn_rcpf(1.f + __expf(-uu)); }
;                     if (ROW_VALID(m)) { const int t = tok0 + 16 * m + fr; u32x2 w; w.x = cvtpk(ov[0], ov[1]); w.y = cvtpk(ov[2], ov[3]);
;                         *(u32x2*)(ACT + (size_t)t * FF + cv0 + 4 * n) = w; }
	v_pk_mul_f32 v[174:175], v[174:175], s[42:43] op_sel_hi:[1,0]
	v_pk_mul_f32 v[176:177], v[216:217], v[224:225]
	v_pk_mul_f32 v[178:179], v[220:221], v[228:229]
	v_exp_f32_e32 v172, v172
	v_exp_f32_e32 v173, v173
	v_exp_f32_e32 v174, v174
	v_exp_f32_e32 v175, v175
	v_pk_add_f32 v[172:173], v[172:173], s[44:45] op_sel_hi:[1,0]
	v_pk_add_f32 v[174:175], v[174:175], s[44:45] op_sel_hi:[1,0]
	v_rcp_f32_e32 v172, v172
	v_rcp_f32_e32 v173, v173
	v_rcp_f32_e32 v174, v174
	v_rcp_f32_e32 v175, v175
	s_mov_b32 s26, 0x0
	v_lshl_add_u64 v[170:171], v[186:187], 0, s[26:27]
	v_pk_mul_f32 v[176:177], v[176:177], v[172:173]
	v_pk_mul_f32 v[178:179], v[178:179], v[174:175]
	s_and_b64 exec, s[28:29], s[14:15]
	v_cvt_pk_bf16_f32 v176, v176, v177
	v_cvt_pk_bf16_f32 v177, v178, v179
	global_store_dwordx2 v[170:171], v[176:177], off offset:0
	s_mov_b64 exec, s[28:29]
	v_pk_mul_f32 v[172:173], v[226:227], s[40:41] op_sel_hi:[1,0]
	v_pk_mul_f32 v[174:175], v[194:195], s[40:41] op_sel_hi:[1,0]
	v_pk_mul_f32 v[172:173], v[226:227], v[172:173]
	v_pk_mul_f32 v[174:175], v[194:195], v[174:175]
	v_pk_fma_f32 v[172:173], v[226:227], v[172:173], v[226:227]
	v_pk_fma_f32 v[174:175], v[194:195], v[174:175], v[194:195]
	v_pk_mul_f32 v[172:173], v[172:173], s[42:43] op_sel_hi:[1,0]
	v_pk_mul_f32 v[174:175], v[174:175], s[42:43] op_sel_hi:[1,0]
	v_pk_mul_f32 v[176:177], v[218:219], v[226:227]
	v_pk_mul_f32 v[178:179], v[222:223], v[194:195]
	v_exp_f32_e32 v172, v172
	v_exp_f32_e32 v173, v173
	v_exp_f32_e32 v174, v174
	v_exp_f32_e32 v175, v175
	v_pk_add_f32 v[172:173], v[172:173], s[44:45] op_sel_hi:[1,0]
	v_pk_add_f32 v[174:175], v[174:175], s[44:45] op_sel_hi:[1,0]
	v_rcp_f32_e32 v172, v172
	v_rcp_f32_e32 v173, v173
	v_rcp_f32_e32 v174, v174
	v_rcp_f32_e32 v175, v175
	s_mov_b32 s26, 0x16000
	v_lshl_add_u64 v[170:171], v[186:187], 0, s[26:27]
	v_pk_mul_f32 v[176:177], v[176:177], v[172:173]
	v_pk_mul_f32 v[178:179], v[178:179], v[174:175]
	v_cvt_pk_bf16_f32 v176, v176, v177
	v_cvt_pk_bf16_f32 v177, v178, v179
	global_store_dwordx2 v[170:171], v[176:177], off offset:0
	v_pk_mul_f32 v[172:173], v[152:153], s[40:41] op_sel_hi:[1,0]
	v_pk_mul_f32 v[174:175], v[154:155], s[40:41] op_sel_hi:[1,0]
	v_pk_mul_f32 v[172:173], v[152:153], v[172:173]
	v_pk_mul_f32 v[174:175], v[154:155], v[174:175]
	v_pk_fma_f32 v[172:173], v[152:153], v[172:173], v[152:153]
	v_pk_fma_f32 v[174:175], v[154:155], v[174:175], v[154:155]
	v_pk_mul_f32 v[172:173], v[172:173], s[42:43] op_sel_hi:[1,0]
	v_pk_mul_f32 v[174:175], v[174:175], s[42:43] op_sel_hi:[1,0]
	v_pk_mul_f32 v[176:177], v[156:157], v[152:153]
	v_pk_mul_f32 v[178:179], v[158:159], v[154:155]
	v_exp_f32_e32 v172, v172
	v_exp_f32_e32 v173, v173
	v_exp_f32_e32 v174, v174
	v_exp_f32_e32 v175, v175
	v_pk_add_f32 v[172:173], v[172:173], s[44:45] op_sel_hi:[1,0]
	v_pk_add_f32 v[174:175], v[174:175], s[44:45] op_sel_hi:[1,0]
	v_rcp_f32_e32 v172, v172
	v_rcp_f32_e32 v173, v173
	v_rcp_f32_e32 v174, v174
	v_rcp_f32_e32 v175, v175
	s_mov_b32 s26, 0x2c000
	v_lshl_add_u64 v[170:171], v[186:187], 0, s[26:27]
	v_pk_mul_f32 v[176:177], v[176:177], v[172:173]
	v_pk_mul_f32 v[178:179], v[178:179], v[174:175]
	v_cvt_pk_bf16_f32 v176, v176, v177
	v_cvt_pk_bf16_f32 v177, v178, v179
	global_store_dwordx2 v[170:171], v[176:177], off offset:0
	v_pk_mul_f32 v[172:173], v[144:145], s[40:41] op_sel_hi:[1,0]
	v_pk_mul_f32 v[174:175], v[146:147], s[40:41] op_sel_hi:[1,0]
	v_pk_mul_f32 v[172:173], v[144:145], v[172:173]
	v_pk_mul_f32 v[174:175], v[146:147], v[174:175]
	v_pk_fma_f32 v[172:173], v[144:145], v[172:173], v[144:145]
	v_pk_fma_f32 v[174:175], v[146:147], v[174:175], v[146:147]
	v_pk_mul_f32 v[172:173], v[172:173], s[42:43] op_sel_hi:[1,0]
	v_pk_mul_f32 v[174:175], v[174:175], s[42:43] op_sel_hi:[1,0]
	v_pk_mul_f32 v[176:177], v[148:149], v[144:145]
	v_pk_mul_f32 v[178:179], v[150:151], v[146:147]
	v_exp_f32_e32 v172, v172
	v_exp_f32_e32 v173, v173
	v_exp_f32_e32 v174, v174
	v_exp_f32_e32 v175, v175
	v_pk_add_f32 v[172:173], v[172:173], s[44:45] op_sel_hi:[1,0]
	v_pk_add_f32 v[174:175], v[174:175], s[44:45] op_sel_hi:[1,0]
	v_rcp_f32_e32 v172, v172
	v_rcp_f32_e32 v173, v173
	v_rcp_f32_e32 v174, v174
	v_rcp_f32_e32 v175, v175
	s_mov_b32 s26, 0x42000
	v_lshl_add_u64 v[170:171], v[186:187], 0, s[26:27]
	v_pk_mul_f32 v[176:177], v[176:177], v[172:173]
	v_pk_mul_f32 v[178:179], v[178:179], v[174:175]
	s_and_b64 exec, s[28:29], s[24:25]
	v_cvt_pk_bf16_f32 v176, v176, v177
	v_cvt_pk_bf16_f32 v177, v178, v179
	global_store_dwordx2 v[170:171], v[176:177], off offset:0
	s_mov_b64 exec, s[28:29]
	v_pk_fma_f32 v[216:217], v[92:93], v[100:101], v[108:109]
	v_pk_fma_f32 v[218:219], v[84:85], v[100:101], v[108:109]
	v_pk_fma_f32 v[220:221], v[94:95], v[102:103], v[110:111]
	v_pk_fma_f32 v[222:223], v[86:87], v[102:103], v[110:111]
	v_pk_fma_f32 v[224:225], v[88:89], v[116:117], v[124:125]
	v_pk_fma_f32 v[226:227], v[80:81], v[116:117], v[124:125]
	v_pk_fma_f32 v[228:229], v[90:91], v[118:119], v[126:127]
	v_pk_fma_f32 v[194:195], v[82:83], v[118:119], v[126:127]
	v_fmac_f32_dpp v216, v92, v96 row_shr:1 row_mask:0xf bank_mask:0xf
	v_fmac_f32_dpp v218, v84, v96 row_shr:1 row_mask:0xf bank_mask:0xf
	v_fmac_f32_dpp v220, v94, v98 row_shr:1 row_mask:0xf bank_mask:0xf
	v_fmac_f32_dpp v222, v86, v98 row_shr:1 row_mask:0xf bank_mask:0xf
	v_fmac_f32_dpp v224, v88, v112 row_shr:1 row_mask:0xf bank_mask:0xf
	v_fmac_f32_dpp v226, v80, v112 row_shr:1 row_mask:0xf bank_mask:0xf
	v_fmac_f32_dpp v228, v90, v114 row_shr:1 row_mask:0xf bank_mask:0xf
	v_fmac_f32_dpp v194, v82, v114 row_shr:1 row_mask:0xf bank_mask:0xf
	v_fmac_f32_dpp v216, v92, v104 row_shl:1 row_mask:0xf bank_mask:0xf
;     DI void operator()(const f32x4 (&acc)[2][2][4][2], const Unit& u, int wr, int wc, int fr_, int fq_) const {
;     ...
;                     CONV_ONE(acc, ai, 0, n, m, zv, vp, vm, vn); CONV_ONE(acc, ai, 1, n, m, zg, gp, gm, gn);
;                     zv = zv + vb; zg = zg + gb;
	v_fmac_f32_dpp v218, v84, v104 row_shl:1 row_mask:0xf bank_mask:0xf
	v_fmac_f32_dpp v220, v94, v106 row_shl:1 row_mask:0xf bank_mask:0xf
	v_fmac_f32_dpp v222, v86, v106 row_shl:1 row_mask:0xf bank_mask:0xf
	v_fmac_f32_dpp v224, v88, v120 row_shl:1 row_mask:0xf bank_mask:0xf
	v_fmac_f32_dpp v226, v80, v120 row_shl:1 row_mask:0xf bank_mask:0xf
	v_fmac_f32_dpp v228, v90, v122 row_shl:1 row_mask:0xf bank_mask:0xf
	v_fmac_f32_dpp v194, v82, v122 row_shl:1 row_mask:0xf bank_mask:0xf
	v_fmac_f32_dpp v216, v84, v204 row_ror:15 row_mask:0xf bank_mask:0xf
	v_fmac_f32_dpp v218, v92, v200 row_ror:1 row_mask:0xf bank_mask:0xf
	v_fmac_f32_dpp v220, v86, v206 row_ror:15 row_mask:0xf bank_mask:0xf
	v_fmac_f32_dpp v222, v94, v202 row_ror:1 row_mask:0xf bank_mask:0xf
	v_fmac_f32_dpp v224, v80, v212 row_ror:15 row_mask:0xf bank_mask:0xf
	v_fmac_f32_dpp v226, v88, v208 row_ror:1 row_mask:0xf bank_mask:0xf
	v_fmac_f32_dpp v228, v82, v214 row_ror:15 row_mask:0xf bank_mask:0xf
	v_fmac_f32_dpp v194, v90, v210 row_ror:1 row_mask:0xf bank_mask:0xf
	v_fmac_f32_dpp v217, v93, v97 row_shr:1 row_mask:0xf bank_mask:0xf
	v_fmac_f32_dpp v218, v76, v204 row_ror:15 row_mask:0xf bank_mask:0xf
	v_fmac_f32_dpp v221, v95, v99 row_shr:1 row_mask:0xf bank_mask:0xf
	v_fmac_f32_dpp v222, v78, v206 row_ror:15 row_mask:0xf bank_mask:0xf
	v_fmac_f32_dpp v225, v89, v113 row_shr:1 row_mask:0xf bank_mask:0xf
	v_fmac_f32_dpp v226, v72, v212 row_ror:15 row_mask:0xf bank_mask:0xf
	v_fmac_f32_dpp v229, v91, v115 row_shr:1 row_mask:0xf bank_mask:0xf
	v_fmac_f32_dpp v194, v74, v214 row_ror:15 row_mask:0xf bank_mask:0xf
	v_fmac_f32_dpp v217, v93, v105 row_shl:1 row_mask:0xf bank_mask:0xf
	v_fmac_f32_dpp v219, v85, v97 row_shr:1 row_mask:0xf bank_mask:0xf
	v_fmac_f32_dpp v221, v95, v107 row_shl:1 row_mask:0xf bank_mask:0xf
	v_fmac_f32_dpp v223, v87, v99 row_shr:1 row_mask:0xf bank_mask:0xf
	v_fmac_f32_dpp v225, v89, v121 row_shl:1 row_mask:0xf bank_mask:0xf
	v_fmac_f32_dpp v227, v81, v113 row_shr:1 row_mask:0xf bank_mask:0xf
	v_fmac_f32_dpp v229, v91, v123 row_shl:1 row_mask:0xf bank_mask:0xf
	v_fmac_f32_dpp v195, v83, v115 row_shr:1 row_mask:0xf bank_mask:0xf
	v_fmac_f32_dpp v217, v85, v205 row_ror:15 row_mask:0xf bank_mask:0xf
	v_fmac_f32_dpp v219, v85, v105 row_shl:1 row_mask:0xf bank_mask:0xf
	v_fmac_f32_dpp v221, v87, v207 row_ror:15 row_mask:0xf bank_mask:0xf
	v_fmac_f32_dpp v223, v87, v107 row_shl:1 row_mask:0xf bank_mask:0xf
	v_fmac_f32_dpp v225, v81, v213 row_ror:15 row_mask:0xf bank_mask:0xf
	v_fmac_f32_dpp v227, v81, v121 row_shl:1 row_mask:0xf bank_mask:0xf
	v_fmac_f32_dpp v229, v83, v215 row_ror:15 row_mask:0xf bank_mask:0xf
	v_fmac_f32_dpp v195, v83, v123 row_shl:1 row_mask:0xf bank_mask:0xf
	v_fmac_f32_dpp v219, v93, v201 row_ror:1 row_mask:0xf bank_mask:0xf
	v_fmac_f32_dpp v223, v95, v203 row_ror:1 row_mask:0xf bank_mask:0xf
	v_fmac_f32_dpp v227, v89, v209 row_ror:1 row_mask:0xf bank_mask:0xf
	v_fmac_f32_dpp v195, v91, v211 row_ror:1 row_mask:0xf bank_mask:0xf
	v_fmac_f32_dpp v219, v77, v205 row_ror:15 row_mask:0xf bank_mask:0xf
	v_fmac_f32_dpp v223, v79, v207 row_ror:15 row_mask:0xf bank_mask:0xf
	v_fmac_f32_dpp v227, v73, v213 row_ror:15 row_mask:0xf bank_mask:0xf
	v_fmac_f32_dpp v195, v75, v215 row_ror:15 row_mask:0xf bank_mask:0xf
	v_pk_fma_f32 v[92:93], v[76:77], v[100:101], v[108:109]
	v_pk_fma_f32 v[94:95], v[78:79], v[102:103], v[110:111]
	v_pk_fma_f32 v[88:89], v[72:73], v[116:117], v[124:125]
	v_pk_fma_f32 v[90:91], v[74:75], v[118:119], v[126:127]
	v_fmac_f32_dpp v92, v76, v96 row_shr:1 row_mask:0xf bank_mask:0xf
	v_fmac_f32_dpp v94, v78, v98 row_shr:1 row_mask:0xf bank_mask:0xf
	v_fmac_f32_dpp v88, v72, v112 row_shr:1 row_mask:0xf bank_mask:0xf
	v_fmac_f32_dpp v90, v74, v114 row_shr:1 row_mask:0xf bank_mask:0xf
	v_fmac_f32_dpp v92, v76, v104 row_shl:1 row_mask:0xf bank_mask:0xf
	v_fmac_f32_dpp v94, v78, v106 row_shl:1 row_mask:0xf bank_mask:0xf
	v_fmac_f32_dpp v88, v72, v120 row_shl:1 row_mask:0xf bank_mask:0xf
	v_fmac_f32_dpp v90, v74, v122 row_shl:1 row_mask:0xf bank_mask:0xf
	v_fmac_f32_dpp v92, v84, v200 row_ror:1 row_mask:0xf bank_mask:0xf
	v_fmac_f32_dpp v94, v86, v202 row_ror:1 row_mask:0xf bank_mask:0xf
	v_fmac_f32_dpp v88, v80, v208 row_ror:1 row_mask:0xf bank_mask:0xf
	v_fmac_f32_dpp v90, v82, v210 row_ror:1 row_mask:0xf bank_mask:0xf
	v_fmac_f32_dpp v92, v68, v204 row_ror:15 row_mask:0xf bank_mask:0xf
	v_fmac_f32_dpp v94, v70, v206 row_ror:15 row_mask:0xf bank_mask:0xf
	v_fmac_f32_dpp v88, v64, v212 row_ror:15 row_mask:0xf bank_mask:0xf
	v_fmac_f32_dpp v90, v66, v214 row_ror:15 row_mask:0xf bank_mask:0xf
	v_fmac_f32_dpp v93, v77, v97 row_shr:1 row_mask:0xf bank_mask:0xf
	v_fmac_f32_dpp v95, v79, v99 row_shr:1 row_mask:0xf bank_mask:0xf
	v_fmac_f32_dpp v89, v73, v113 row_shr:1 row_mask:0xf bank_mask:0xf
	v_fmac_f32_dpp v91, v75, v115 row_shr:1 row_mask:0xf bank_mask:0xf
	v_fmac_f32_dpp v93, v77, v105 row_shl:1 row_mask:0xf bank_mask:0xf
	v_fmac_f32_dpp v95, v79, v107 row_shl:1 row_mask:0xf bank_mask:0xf
	v_fmac_f32_dpp v89, v73, v121 row_shl:1 row_mask:0xf bank_mask:0xf
	v_fmac_f32_dpp v91, v75, v123 row_shl:1 row_mask:0xf bank_mask:0xf
	v_fmac_f32_dpp v93, v85, v201 row_ror:1 row_mask:0xf bank_mask:0xf
	v_fmac_f32_dpp v95, v87, v203 row_ror:1 row_mask:0xf bank_mask:0xf
	v_fmac_f32_dpp v89, v81, v209 row_ror:1 row_mask:0xf bank_mask:0xf
	v_fmac_f32_dpp v91, v83, v211 row_ror:1 row_mask:0xf bank_mask:0xf
	v_fmac_f32_dpp v93, v69, v205 row_ror:15 row_mask:0xf bank_mask:0xf
	v_fmac_f32_dpp v95, v71, v207 row_ror:15 row_mask:0xf bank_mask:0xf
	v_fmac_f32_dpp v89, v65, v213 row_ror:15 row_mask:0xf bank_mask:0xf
	v_fmac_f32_dpp v91, v67, v215 row_ror:15 row_mask:0xf bank_mask:0xf
; DI unsigned cvtpk(float lo, float hi) { unsigned r; asm volatile("v_cvt_pk_bf16_f32 %0, %1, %2" : "=v"(r) : "v"(lo), "v"(hi)); return r; }
;     DI void operator()(const f32x4 (&acc)[2][2][4][2], const Unit& u, int wr, int wc, int fr_, int fq_) const {
;     ...
;                 for (int m = 0; m < 4; ++m) { f32x4 zv, zg;
;                     CONV_ONE(acc, ai, 0, n, m, zv, vp, vm, vn); CONV_ONE(acc, ai, 1, n, m, zg, gp, gm, gn);
;                     zv = zv + vb; zg = zg + gb;
;                     float ov[4];
; #pragma unroll
;                     for (int e = 0; e < 4; ++e) { const float x = zg[e]; const float uu = 1.5957691216f * (x + 0.044715f * x * x * x);
;                         ov[e] = zv[e] * x * __builtin_amdgcn_rcpf(1.f + __expf(-uu)); }
;                     if (ROW_VALID(m)) { const int t = tok0 + 16 * m + fr; u32x2 w; w.x = cvtpk(ov[0], ov[1]); w.y = cvtpk(ov[2], ov[3]);
;                         *(u32x2*)(ACT + (size_t)t * FF + cv0 + 4 * n) = w; }
	v_pk_fma_f32 v[84:85], v[68:69], v[100:101], v[108:109]
	v_pk_fma_f32 v[86:87], v[70:71], v[102:103], v[110:111]
	v_pk_fma_f32 v[80:81], v[64:65], v[116:117], v[124:125]
	v_pk_fma_f32 v[82:83], v[66:67], v[118:119], v[126:127]
	v_fmac_f32_dpp v84, v68, v96 row_shr:1 row_mask:0xf bank_mask:0xf
	v_fmac_f32_dpp v86, v70, v98 row_shr:1 row_mask:0xf bank_mask:0xf
	v_fmac_f32_dpp v80, v64, v112 row_shr:1 row_mask:0xf bank_mask:0xf
	v_fmac_f32_dpp v82, v66, v114 row_shr:1 row_mask:0xf bank_mask:0xf
	v_fmac_f32_dpp v84, v68, v104 row_shl:1 row_mask:0xf bank_mask:0xf
	v_fmac_f32_dpp v86, v70, v106 row_shl:1 row_mask:0xf bank_mask:0xf
	v_fmac_f32_dpp v80, v64, v120 row_shl:1 row_mask:0xf bank_mask:0xf
	v_fmac_f32_dpp v82, v66, v122 row_shl:1 row_mask:0xf bank_mask:0xf
	v_fmac_f32_dpp v84, v76, v200 row_ror:1 row_mask:0xf bank_mask:0xf
	v_fmac_f32_dpp v86, v78, v202 row_ror:1 row_mask:0xf bank_mask:0xf
	v_fmac_f32_dpp v80, v72, v208 row_ror:1 row_mask:0xf bank_mask:0xf
	v_fmac_f32_dpp v82, v74, v210 row_ror:1 row_mask:0xf bank_mask:0xf
	v_fmac_f32_dpp v85, v69, v97 row_shr:1 row_mask:0xf bank_mask:0xf
	v_fmac_f32_dpp v87, v71, v99 row_shr:1 row_mask:0xf bank_mask:0xf
	v_fmac_f32_dpp v81, v65, v113 row_shr:1 row_mask:0xf bank_mask:0xf
	v_fmac_f32_dpp v83, v67, v115 row_shr:1 row_mask:0xf bank_mask:0xf
	v_fmac_f32_dpp v85, v69, v105 row_shl:1 row_mask:0xf bank_mask:0xf
	v_fmac_f32_dpp v87, v71, v107 row_shl:1 row_mask:0xf bank_mask:0xf
	v_fmac_f32_dpp v81, v65, v121 row_shl:1 row_mask:0xf bank_mask:0xf
	v_fmac_f32_dpp v83, v67, v123 row_shl:1 row_mask:0xf bank_mask:0xf
	v_fmac_f32_dpp v85, v77, v201 row_ror:1 row_mask:0xf bank_mask:0xf
	v_fmac_f32_dpp v87, v79, v203 row_ror:1 row_mask:0xf bank_mask:0xf
	v_fmac_f32_dpp v81, v73, v209 row_ror:1 row_mask:0xf bank_mask:0xf
	v_fmac_f32_dpp v83, v75, v211 row_ror:1 row_mask:0xf bank_mask:0xf
	v_pk_mul_f32 v[172:173], v[224:225], s[40:41] op_sel_hi:[1,0]
	v_pk_mul_f32 v[174:175], v[228:229], s[40:41] op_sel_hi:[1,0]
	v_pk_mul_f32 v[172:173], v[224:225], v[172:173]
	v_pk_mul_f32 v[174:175], v[228:229], v[174:175]
	v_pk_fma_f32 v[172:173], v[224:225], v[172:173], v[224:225]
	v_pk_fma_f32 v[174:175], v[228:229], v[174:175], v[228:229]
	v_pk_mul_f32 v[172:173], v[172:173], s[42:43] op_sel_hi:[1,0]
	v_pk_mul_f32 v[174:175], v[174:175], s[42:43] op_sel_hi:[1,0]
	v_pk_mul_f32 v[176:177], v[216:217], v[224:225]
	v_pk_mul_f32 v[178:179], v[220:221], v[228:229]
	v_exp_f32_e32 v172, v172
	v_exp_f32_e32 v173, v173
	v_exp_f32_e32 v174, v174
	v_exp_f32_e32 v175, v175
	v_pk_add_f32 v[172:173], v[172:173], s[44:45] op_sel_hi:[1,0]
	v_pk_add_f32 v[174:175], v[174:175], s[44:45] op_sel_hi:[1,0]
	v_rcp_f32_e32 v172, v172
	v_rcp_f32_e32 v173, v173
	v_rcp_f32_e32 v174, v174
	v_rcp_f32_e32 v175, v175
	s_mov_b32 s26, 0xaa800
	v_lshl_add_u64 v[170:171], v[186:187], 0, s[26:27]
	v_pk_mul_f32 v[176:177], v[176:177], v[172:173]
	v_pk_mul_f32 v[178:179], v[178:179], v[174:175]
	s_and_b64 exec, s[28:29], s[14:15]
	v_cvt_pk_bf16_f32 v176, v176, v177
	v_cvt_pk_bf16_f32 v177, v178, v179
	global_store_dwordx2 v[170:171], v[176:177], off offset:0
	s_mov_b64 exec, s[28:29]
	v_pk_mul_f32 v[172:173], v[226:227], s[40:41] op_sel_hi:[1,0]
	v_pk_mul_f32 v[174:175], v[194:195], s[40:41] op_sel_hi:[1,0]
	v_pk_mul_f32 v[172:173], v[226:227], v[172:173]
	v_pk_mul_f32 v[174:175], v[194:195], v[174:175]
	v_pk_fma_f32 v[172:173], v[226:227], v[172:173], v[226:227]
	v_pk_fma_f32 v[174:175], v[194:195], v[174:175], v[194:195]
	v_pk_mul_f32 v[172:173], v[172:173], s[42:43] op_sel_hi:[1,0]
	v_pk_mul_f32 v[174:175], v[174:175], s[42:43] op_sel_hi:[1,0]
	v_pk_mul_f32 v[176:177], v[218:219], v[226:227]
	v_pk_mul_f32 v[178:179], v[222:223], v[194:195]
	v_exp_f32_e32 v172, v172
	v_exp_f32_e32 v173, v173
	v_exp_f32_e32 v174, v174
	v_exp_f32_e32 v175, v175
	v_pk_add_f32 v[172:173], v[172:173], s[44:45] op_sel_hi:[1,0]
	v_pk_add_f32 v[174:175], v[174:175], s[44:45] op_sel_hi:[1,0]
	v_rcp_f32_e32 v172, v172
	v_rcp_f32_e32 v173, v173
	v_rcp_f32_e32 v174, v174
	v_rcp_f32_e32 v175, v175
	s_mov_b32 s26, 0xc0800
	v_lshl_add_u64 v[170:171], v[186:187], 0, s[26:27]
	v_pk_mul_f32 v[176:177], v[176:177], v[172:173]
	v_pk_mul_f32 v[178:179], v[178:179], v[174:175]
	v_cvt_pk_bf16_f32 v176, v176, v177
	v_cvt_pk_bf16_f32 v177, v178, v179
	global_store_dwordx2 v[170:171], v[176:177], off offset:0
	v_pk_mul_f32 v[172:173], v[88:89], s[40:41] op_sel_hi:[1,0]
	v_pk_mul_f32 v[174:175], v[90:91], s[40:41] op_sel_hi:[1,0]
	v_pk_mul_f32 v[172:173], v[88:89], v[172:173]
	v_pk_mul_f32 v[174:175], v[90:91], v[174:175]
	v_pk_fma_f32 v[172:173], v[88:89], v[172:173], v[88:89]
	v_pk_fma_f32 v[174:175], v[90:91], v[174:175], v[90:91]
	v_pk_mul_f32 v[172:173], v[172:173], s[42:43] op_sel_hi:[1,0]
	v_pk_mul_f32 v[174:175], v[174:175], s[42:43] op_sel_hi:[1,0]
	v_pk_mul_f32 v[176:177], v[92:93], v[88:89]
	v_pk_mul_f32 v[178:179], v[94:95], v[90:91]
	v_exp_f32_e32 v172, v172
	v_exp_f32_e32 v173, v173
	v_exp_f32_e32 v174, v174
	v_exp_f32_e32 v175, v175
	v_pk_add_f32 v[172:173], v[172:173], s[44:45] op_sel_hi:[1,0]
	v_pk_add_f32 v[174:175], v[174:175], s[44:45] op_sel_hi:[1,0]
	v_rcp_f32_e32 v172, v172
	v_rcp_f32_e32 v173, v173
	v_rcp_f32_e32 v174, v174
	v_rcp_f32_e32 v175, v175
	s_mov_b32 s26, 0xd6800
	v_lshl_add_u64 v[170:171], v[186:187], 0, s[26:27]
	v_pk_mul_f32 v[176:177], v[176:177], v[172:173]
	v_pk_mul_f32 v[178:179], v[178:179], v[174:175]
	v_cvt_pk_bf16_f32 v176, v176, v177
	v_cvt_pk_bf16_f32 v177, v178, v179
	global_store_dwordx2 v[170:171], v[176:177], off offset:0
	v_pk_mul_f32 v[172:173], v[80:81], s[40:41] op_sel_hi:[1,0]
	v_pk_mul_f32 v[174:175], v[82:83], s[40:41] op_sel_hi:[1,0]
; DI unsigned cvtpk(float lo, float hi) { unsigned r; asm volatile("v_cvt_pk_bf16_f32 %0, %1, %2" : "=v"(r) : "v"(lo), "v"(hi)); return r; }
;     DI void operator()(const f32x4 (&acc)[2][2][4][2], const Unit& u, int wr, int wc, int fr_, int fq_) const {
;     ...
;         for (int n = 0; n < 2; ++n) {
;             const int sv = cv0 + 4 * n, sg = FF + cv0 + 4 * n;
;             const f32x4 vp = *(const f32x4*)(cw + sv), vm = *(const f32x4*)(cw + NUP + sv), vn = *(const f32x4*)(cw + 2 * NUP + sv), vb = *(const f32x4*)(cb + sv);
;             const f32x4 gp = *(const f32x4*)(cw + sg), gm = *(const f32x4*)(cw + NUP + sg), gn = *(const f32x4*)(cw + 2 * NUP + sg), gb = *(const f32x4*)(cb + sg);
; #pragma unroll
;             for (int ai = 0; ai < 2; ++ai) {
;                 const int tok0 = u.pm * 248 + (2 * ai + wr) * 62 - 1;
; #pragma unroll
;                 for (int m = 0; m < 4; ++m) { f32x4 zv, zg;
;                     CONV_ONE(acc, ai, 0, n, m, zv, vp, vm, vn); CONV_ONE(acc, ai, 1, n, m, zg, gp, gm, gn);
;                     zv = zv + vb; zg = zg + gb;
;                     float ov[4];
; #pragma unroll
;                     for (int e = 0; e < 4; ++e) { const float x = zg[e]; const float uu = 1.5957691216f * (x + 0.044715f * x * x * x);
;                         ov[e] = zv[e] * x * __builtin_amdgcn_rcpf(1.f + __expf(-uu)); }
;                     if (ROW_VALID(m)) { const int t = tok0 + 16 * m + fr; u32x2 w; w.x = cvtpk(ov[0], ov[1]); w.y = cvtpk(ov[2], ov[3]);
;                         *(u32x2*)(ACT + (size_t)t * FF + cv0 + 4 * n) = w; }
	v_pk_mul_f32 v[172:173], v[80:81], v[172:173]
	v_pk_mul_f32 v[174:175], v[82:83], v[174:175]
	v_pk_fma_f32 v[172:173], v[80:81], v[172:173], v[80:81]
	v_pk_fma_f32 v[174:175], v[82:83], v[174:175], v[82:83]
	v_pk_mul_f32 v[172:173], v[172:173], s[42:43] op_sel_hi:[1,0]
	v_pk_mul_f32 v[174:175], v[174:175], s[42:43] op_sel_hi:[1,0]
	v_pk_mul_f32 v[176:177], v[84:85], v[80:81]
	v_pk_mul_f32 v[178:179], v[86:87], v[82:83]
	v_exp_f32_e32 v172, v172
	v_exp_f32_e32 v173, v173
	v_exp_f32_e32 v174, v174
	v_exp_f32_e32 v175, v175
	v_pk_add_f32 v[172:173], v[172:173], s[44:45] op_sel_hi:[1,0]
	v_pk_add_f32 v[174:175], v[174:175], s[44:45] op_sel_hi:[1,0]
	v_rcp_f32_e32 v172, v172
	v_rcp_f32_e32 v173, v173
	v_rcp_f32_e32 v174, v174
	v_rcp_f32_e32 v175, v175
	s_mov_b32 s26, 0xec800
	v_lshl_add_u64 v[170:171], v[186:187], 0, s[26:27]
	v_pk_mul_f32 v[176:177], v[176:177], v[172:173]
	v_pk_mul_f32 v[178:179], v[178:179], v[174:175]
	s_and_b64 exec, s[28:29], s[24:25]
	v_cvt_pk_bf16_f32 v176, v176, v177
	v_cvt_pk_bf16_f32 v177, v178, v179
	global_store_dwordx2 v[170:171], v[176:177], off offset:0
	s_mov_b64 exec, s[28:29]
	ds_read_b128 v[96:99], v188 offset:16
	ds_read_b128 v[100:103], v188 offset:528
	ds_read_b128 v[104:107], v188 offset:1040
	ds_read_b128 v[108:111], v188 offset:3088
	ds_read_b128 v[112:115], v188 offset:1552
	ds_read_b128 v[116:119], v188 offset:2064
	ds_read_b128 v[120:123], v188 offset:2576
	ds_read_b128 v[124:127], v188 offset:3600
	s_waitcnt lgkmcnt(0)
	v_cndmask_b32_e64 v200, 0, v96, s[10:11]
	v_cndmask_b32_e64 v204, 0, v104, s[12:13]
	v_cndmask_b32_e64 v208, 0, v112, s[10:11]
	v_cndmask_b32_e64 v212, 0, v120, s[12:13]
	v_cndmask_b32_e64 v201, 0, v97, s[10:11]
	v_cndmask_b32_e64 v205, 0, v105, s[12:13]
	v_cndmask_b32_e64 v209, 0, v113, s[10:11]
	v_cndmask_b32_e64 v213, 0, v121, s[12:13]
	v_cndmask_b32_e64 v202, 0, v98, s[10:11]
	v_cndmask_b32_e64 v206, 0, v106, s[12:13]
	v_cndmask_b32_e64 v210, 0, v114, s[10:11]
	v_cndmask_b32_e64 v214, 0, v122, s[12:13]
	v_cndmask_b32_e64 v203, 0, v99, s[10:11]
	v_cndmask_b32_e64 v207, 0, v107, s[12:13]
	v_cndmask_b32_e64 v211, 0, v115, s[10:11]
	v_cndmask_b32_e64 v215, 0, v123, s[12:13]
	v_pk_fma_f32 v[216:217], v[60:61], v[100:101], v[108:109]
	v_pk_fma_f32 v[218:219], v[52:53], v[100:101], v[108:109]
	v_pk_fma_f32 v[220:221], v[62:63], v[102:103], v[110:111]
	v_pk_fma_f32 v[222:223], v[54:55], v[102:103], v[110:111]
	v_pk_fma_f32 v[224:225], v[56:57], v[116:117], v[124:125]
	v_pk_fma_f32 v[226:227], v[48:49], v[116:117], v[124:125]
	v_pk_fma_f32 v[228:229], v[58:59], v[118:119], v[126:127]
	v_pk_fma_f32 v[194:195], v[50:51], v[118:119], v[126:127]
	v_fmac_f32_dpp v216, v60, v96 row_shr:1 row_mask:0xf bank_mask:0xf
	v_fmac_f32_dpp v218, v52, v96 row_shr:1 row_mask:0xf bank_mask:0xf
	v_fmac_f32_dpp v220, v62, v98 row_shr:1 row_mask:0xf bank_mask:0xf
	v_fmac_f32_dpp v222, v54, v98 row_shr:1 row_mask:0xf bank_mask:0xf
	v_fmac_f32_dpp v224, v56, v112 row_shr:1 row_mask:0xf bank_mask:0xf
	v_fmac_f32_dpp v226, v48, v112 row_shr:1 row_mask:0xf bank_mask:0xf
	v_fmac_f32_dpp v228, v58, v114 row_shr:1 row_mask:0xf bank_mask:0xf
	v_fmac_f32_dpp v194, v50, v114 row_shr:1 row_mask:0xf bank_mask:0xf
	v_fmac_f32_dpp v216, v60, v104 row_shl:1 row_mask:0xf bank_mask:0xf
	v_fmac_f32_dpp v218, v52, v104 row_shl:1 row_mask:0xf bank_mask:0xf
	v_fmac_f32_dpp v220, v62, v106 row_shl:1 row_mask:0xf bank_mask:0xf
	v_fmac_f32_dpp v222, v54, v106 row_shl:1 row_mask:0xf bank_mask:0xf
	v_fmac_f32_dpp v224, v56, v120 row_shl:1 row_mask:0xf bank_mask:0xf
	v_fmac_f32_dpp v226, v48, v120 row_shl:1 row_mask:0xf bank_mask:0xf
	v_fmac_f32_dpp v228, v58, v122 row_shl:1 row_mask:0xf bank_mask:0xf
	v_fmac_f32_dpp v194, v50, v122 row_shl:1 row_mask:0xf bank_mask:0xf
	v_fmac_f32_dpp v216, v52, v204 row_ror:15 row_mask:0xf bank_mask:0xf
	v_fmac_f32_dpp v218, v60, v200 row_ror:1 row_mask:0xf bank_mask:0xf
	v_fmac_f32_dpp v220, v54, v206 row_ror:15 row_mask:0xf bank_mask:0xf
	v_fmac_f32_dpp v222, v62, v202 row_ror:1 row_mask:0xf bank_mask:0xf
	v_fmac_f32_dpp v224, v48, v212 row_ror:15 row_mask:0xf bank_mask:0xf
	v_fmac_f32_dpp v226, v56, v208 row_ror:1 row_mask:0xf bank_mask:0xf
	v_fmac_f32_dpp v228, v50, v214 row_ror:15 row_mask:0xf bank_mask:0xf
	v_fmac_f32_dpp v194, v58, v210 row_ror:1 row_mask:0xf bank_mask:0xf
	v_fmac_f32_dpp v217, v61, v97 row_shr:1 row_mask:0xf bank_mask:0xf
	v_fmac_f32_dpp v218, v44, v204 row_ror:15 row_mask:0xf bank_mask:0xf
	v_fmac_f32_dpp v221, v63, v99 row_shr:1 row_mask:0xf bank_mask:0xf
	v_fmac_f32_dpp v222, v46, v206 row_ror:15 row_mask:0xf bank_mask:0xf
	v_fmac_f32_dpp v225, v57, v113 row_shr:1 row_mask:0xf bank_mask:0xf
	v_fmac_f32_dpp v226, v40, v212 row_ror:15 row_mask:0xf bank_mask:0xf
	v_fmac_f32_dpp v229, v59, v115 row_shr:1 row_mask:0xf bank_mask:0xf
	v_fmac_f32_dpp v194, v42, v214 row_ror:15 row_mask:0xf bank_mask:0xf
	v_fmac_f32_dpp v217, v61, v105 row_shl:1 row_mask:0xf bank_mask:0xf
	v_fmac_f32_dpp v219, v53, v97 row_shr:1 row_mask:0xf bank_mask:0xf
	v_fmac_f32_dpp v221, v63, v107 row_shl:1 row_mask:0xf bank_mask:0xf
	v_fmac_f32_dpp v223, v55, v99 row_shr:1 row_mask:0xf bank_mask:0xf
	v_fmac_f32_dpp v225, v57, v121 row_shl:1 row_mask:0xf bank_mask:0xf
	v_fmac_f32_dpp v227, v49, v113 row_shr:1 row_mask:0xf bank_mask:0xf
	v_fmac_f32_dpp v229, v59, v123 row_shl:1 row_mask:0xf bank_mask:0xf
	v_fmac_f32_dpp v195, v51, v115 row_shr:1 row_mask:0xf bank_mask:0xf
	v_fmac_f32_dpp v217, v53, v205 row_ror:15 row_mask:0xf bank_mask:0xf
	v_fmac_f32_dpp v219, v53, v105 row_shl:1 row_mask:0xf bank_mask:0xf
	v_fmac_f32_dpp v221, v55, v207 row_ror:15 row_mask:0xf bank_mask:0xf
;     DI void operator()(const f32x4 (&acc)[2][2][4][2], const Unit& u, int wr, int wc, int fr_, int fq_) const {
;     ...
;                     CONV_ONE(acc, ai, 0, n, m, zv, vp, vm, vn); CONV_ONE(acc, ai, 1, n, m, zg, gp, gm, gn);
;                     zv = zv + vb; zg = zg + gb;
	v_fmac_f32_dpp v223, v55, v107 row_shl:1 row_mask:0xf bank_mask:0xf
	v_fmac_f32_dpp v225, v49, v213 row_ror:15 row_mask:0xf bank_mask:0xf
	v_fmac_f32_dpp v227, v49, v121 row_shl:1 row_mask:0xf bank_mask:0xf
	v_fmac_f32_dpp v229, v51, v215 row_ror:15 row_mask:0xf bank_mask:0xf
	v_fmac_f32_dpp v195, v51, v123 row_shl:1 row_mask:0xf bank_mask:0xf
	v_fmac_f32_dpp v219, v61, v201 row_ror:1 row_mask:0xf bank_mask:0xf
	v_fmac_f32_dpp v223, v63, v203 row_ror:1 row_mask:0xf bank_mask:0xf
	v_fmac_f32_dpp v227, v57, v209 row_ror:1 row_mask:0xf bank_mask:0xf
	v_fmac_f32_dpp v195, v59, v211 row_ror:1 row_mask:0xf bank_mask:0xf
	v_fmac_f32_dpp v219, v45, v205 row_ror:15 row_mask:0xf bank_mask:0xf
	v_fmac_f32_dpp v223, v47, v207 row_ror:15 row_mask:0xf bank_mask:0xf
	v_fmac_f32_dpp v227, v41, v213 row_ror:15 row_mask:0xf bank_mask:0xf
	v_fmac_f32_dpp v195, v43, v215 row_ror:15 row_mask:0xf bank_mask:0xf
	v_pk_fma_f32 v[60:61], v[44:45], v[100:101], v[108:109]
	v_pk_fma_f32 v[62:63], v[46:47], v[102:103], v[110:111]
	v_pk_fma_f32 v[56:57], v[40:41], v[116:117], v[124:125]
	v_pk_fma_f32 v[58:59], v[42:43], v[118:119], v[126:127]
	v_fmac_f32_dpp v60, v44, v96 row_shr:1 row_mask:0xf bank_mask:0xf
	v_fmac_f32_dpp v62, v46, v98 row_shr:1 row_mask:0xf bank_mask:0xf
	v_fmac_f32_dpp v56, v40, v112 row_shr:1 row_mask:0xf bank_mask:0xf
	v_fmac_f32_dpp v58, v42, v114 row_shr:1 row_mask:0xf bank_mask:0xf
	v_fmac_f32_dpp v60, v44, v104 row_shl:1 row_mask:0xf bank_mask:0xf
	v_fmac_f32_dpp v62, v46, v106 row_shl:1 row_mask:0xf bank_mask:0xf
	v_fmac_f32_dpp v56, v40, v120 row_shl:1 row_mask:0xf bank_mask:0xf
	v_fmac_f32_dpp v58, v42, v122 row_shl:1 row_mask:0xf bank_mask:0xf
	v_fmac_f32_dpp v60, v52, v200 row_ror:1 row_mask:0xf bank_mask:0xf
	v_fmac_f32_dpp v62, v54, v202 row_ror:1 row_mask:0xf bank_mask:0xf
	v_fmac_f32_dpp v56, v48, v208 row_ror:1 row_mask:0xf bank_mask:0xf
	v_fmac_f32_dpp v58, v50, v210 row_ror:1 row_mask:0xf bank_mask:0xf
	v_fmac_f32_dpp v60, v36, v204 row_ror:15 row_mask:0xf bank_mask:0xf
	v_fmac_f32_dpp v62, v38, v206 row_ror:15 row_mask:0xf bank_mask:0xf
	v_fmac_f32_dpp v56, v32, v212 row_ror:15 row_mask:0xf bank_mask:0xf
	v_fmac_f32_dpp v58, v34, v214 row_ror:15 row_mask:0xf bank_mask:0xf
	v_fmac_f32_dpp v61, v45, v97 row_shr:1 row_mask:0xf bank_mask:0xf
	v_fmac_f32_dpp v63, v47, v99 row_shr:1 row_mask:0xf bank_mask:0xf
	v_fmac_f32_dpp v57, v41, v113 row_shr:1 row_mask:0xf bank_mask:0xf
	v_fmac_f32_dpp v59, v43, v115 row_shr:1 row_mask:0xf bank_mask:0xf
	v_fmac_f32_dpp v61, v45, v105 row_shl:1 row_mask:0xf bank_mask:0xf
	v_fmac_f32_dpp v63, v47, v107 row_shl:1 row_mask:0xf bank_mask:0xf
	v_fmac_f32_dpp v57, v41, v121 row_shl:1 row_mask:0xf bank_mask:0xf
	v_fmac_f32_dpp v59, v43, v123 row_shl:1 row_mask:0xf bank_mask:0xf
	v_fmac_f32_dpp v61, v53, v201 row_ror:1 row_mask:0xf bank_mask:0xf
	v_fmac_f32_dpp v63, v55, v203 row_ror:1 row_mask:0xf bank_mask:0xf
	v_fmac_f32_dpp v57, v49, v209 row_ror:1 row_mask:0xf bank_mask:0xf
	v_fmac_f32_dpp v59, v51, v211 row_ror:1 row_mask:0xf bank_mask:0xf
	v_fmac_f32_dpp v61, v37, v205 row_ror:15 row_mask:0xf bank_mask:0xf
	v_fmac_f32_dpp v63, v39, v207 row_ror:15 row_mask:0xf bank_mask:0xf
	v_fmac_f32_dpp v57, v33, v213 row_ror:15 row_mask:0xf bank_mask:0xf
	v_fmac_f32_dpp v59, v35, v215 row_ror:15 row_mask:0xf bank_mask:0xf
	v_pk_fma_f32 v[52:53], v[36:37], v[100:101], v[108:109]
	v_pk_fma_f32 v[54:55], v[38:39], v[102:103], v[110:111]
	v_pk_fma_f32 v[48:49], v[32:33], v[116:117], v[124:125]
	v_pk_fma_f32 v[50:51], v[34:35], v[118:119], v[126:127]
	v_fmac_f32_dpp v52, v36, v96 row_shr:1 row_mask:0xf bank_mask:0xf
	v_fmac_f32_dpp v54, v38, v98 row_shr:1 row_mask:0xf bank_mask:0xf
	v_fmac_f32_dpp v48, v32, v112 row_shr:1 row_mask:0xf bank_mask:0xf
	v_fmac_f32_dpp v50, v34, v114 row_shr:1 row_mask:0xf bank_mask:0xf
	v_fmac_f32_dpp v52, v36, v104 row_shl:1 row_mask:0xf bank_mask:0xf
	v_fmac_f32_dpp v54, v38, v106 row_shl:1 row_mask:0xf bank_mask:0xf
	v_fmac_f32_dpp v48, v32, v120 row_shl:1 row_mask:0xf bank_mask:0xf
	v_fmac_f32_dpp v50, v34, v122 row_shl:1 row_mask:0xf bank_mask:0xf
	v_fmac_f32_dpp v52, v44, v200 row_ror:1 row_mask:0xf bank_mask:0xf
	v_fmac_f32_dpp v54, v46, v202 row_ror:1 row_mask:0xf bank_mask:0xf
	v_fmac_f32_dpp v48, v40, v208 row_ror:1 row_mask:0xf bank_mask:0xf
	v_fmac_f32_dpp v50, v42, v210 row_ror:1 row_mask:0xf bank_mask:0xf
	v_fmac_f32_dpp v53, v37, v97 row_shr:1 row_mask:0xf bank_mask:0xf
	v_fmac_f32_dpp v55, v39, v99 row_shr:1 row_mask:0xf bank_mask:0xf
	v_fmac_f32_dpp v49, v33, v113 row_shr:1 row_mask:0xf bank_mask:0xf
	v_fmac_f32_dpp v51, v35, v115 row_shr:1 row_mask:0xf bank_mask:0xf
	v_fmac_f32_dpp v53, v37, v105 row_shl:1 row_mask:0xf bank_mask:0xf
	v_fmac_f32_dpp v55, v39, v107 row_shl:1 row_mask:0xf bank_mask:0xf
	v_fmac_f32_dpp v49, v33, v121 row_shl:1 row_mask:0xf bank_mask:0xf
	v_fmac_f32_dpp v51, v35, v123 row_shl:1 row_mask:0xf bank_mask:0xf
	v_fmac_f32_dpp v53, v45, v201 row_ror:1 row_mask:0xf bank_mask:0xf
	v_fmac_f32_dpp v55, v47, v203 row_ror:1 row_mask:0xf bank_mask:0xf
	v_fmac_f32_dpp v49, v41, v209 row_ror:1 row_mask:0xf bank_mask:0xf
	v_fmac_f32_dpp v51, v43, v211 row_ror:1 row_mask:0xf bank_mask:0xf
	v_pk_mul_f32 v[172:173], v[224:225], s[40:41] op_sel_hi:[1,0]
	v_pk_mul_f32 v[174:175], v[228:229], s[40:41] op_sel_hi:[1,0]
	v_pk_mul_f32 v[172:173], v[224:225], v[172:173]
	v_pk_mul_f32 v[174:175], v[228:229], v[174:175]
	v_pk_fma_f32 v[172:173], v[224:225], v[172:173], v[224:225]
	v_pk_fma_f32 v[174:175], v[228:229], v[174:175], v[228:229]
	v_pk_mul_f32 v[172:173], v[172:173], s[42:43] op_sel_hi:[1,0]
	v_pk_mul_f32 v[174:175], v[174:175], s[42:43] op_sel_hi:[1,0]
; DI unsigned cvtpk(float lo, float hi) { unsigned r; asm volatile("v_cvt_pk_bf16_f32 %0, %1, %2" : "=v"(r) : "v"(lo), "v"(hi)); return r; }
;     DI void operator()(const f32x4 (&acc)[2][2][4][2], const Unit& u, int wr, int wc, int fr_, int fq_) const {
;     ...
;                 for (int m = 0; m < 4; ++m) { f32x4 zv, zg;
;                     CONV_ONE(acc, ai, 0, n, m, zv, vp, vm, vn); CONV_ONE(acc, ai, 1, n, m, zg, gp, gm, gn);
;                     zv = zv + vb; zg = zg + gb;
;                     float ov[4];
; #pragma unroll
;                     for (int e = 0; e < 4; ++e) { const float x = zg[e]; const float uu = 1.5957691216f * (x + 0.044715f * x * x * x);
;                         ov[e] = zv[e] * x * __builtin_amdgcn_rcpf(1.f + __expf(-uu)); }
;                     if (ROW_VALID(m)) { const int t = tok0 + 16 * m + fr; u32x2 w; w.x = cvtpk(ov[0], ov[1]); w.y = cvtpk(ov[2], ov[3]);
;                         *(u32x2*)(ACT + (size_t)t * FF + cv0 + 4 * n) = w; }
	v_pk_mul_f32 v[176:177], v[216:217], v[224:225]
	v_pk_mul_f32 v[178:179], v[220:221], v[228:229]
	v_exp_f32_e32 v172, v172
	v_exp_f32_e32 v173, v173
	v_exp_f32_e32 v174, v174
	v_exp_f32_e32 v175, v175
	v_pk_add_f32 v[172:173], v[172:173], s[44:45] op_sel_hi:[1,0]
	v_pk_add_f32 v[174:175], v[174:175], s[44:45] op_sel_hi:[1,0]
	v_rcp_f32_e32 v172, v172
	v_rcp_f32_e32 v173, v173
	v_rcp_f32_e32 v174, v174
	v_rcp_f32_e32 v175, v175
	s_mov_b32 s26, 0x0
	v_lshl_add_u64 v[170:171], v[186:187], 0, s[26:27]
	v_pk_mul_f32 v[176:177], v[176:177], v[172:173]
	v_pk_mul_f32 v[178:179], v[178:179], v[174:175]
	s_and_b64 exec, s[28:29], s[14:15]
	v_cvt_pk_bf16_f32 v176, v176, v177
	v_cvt_pk_bf16_f32 v177, v178, v179
	global_store_dwordx2 v[170:171], v[176:177], off offset:8
	s_mov_b64 exec, s[28:29]
	v_pk_mul_f32 v[172:173], v[226:227], s[40:41] op_sel_hi:[1,0]
	v_pk_mul_f32 v[174:175], v[194:195], s[40:41] op_sel_hi:[1,0]
	v_pk_mul_f32 v[172:173], v[226:227], v[172:173]
	v_pk_mul_f32 v[174:175], v[194:195], v[174:175]
	v_pk_fma_f32 v[172:173], v[226:227], v[172:173], v[226:227]
	v_pk_fma_f32 v[174:175], v[194:195], v[174:175], v[194:195]
	v_pk_mul_f32 v[172:173], v[172:173], s[42:43] op_sel_hi:[1,0]
	v_pk_mul_f32 v[174:175], v[174:175], s[42:43] op_sel_hi:[1,0]
	v_pk_mul_f32 v[176:177], v[218:219], v[226:227]
	v_pk_mul_f32 v[178:179], v[222:223], v[194:195]
	v_exp_f32_e32 v172, v172
	v_exp_f32_e32 v173, v173
	v_exp_f32_e32 v174, v174
	v_exp_f32_e32 v175, v175
	v_pk_add_f32 v[172:173], v[172:173], s[44:45] op_sel_hi:[1,0]
	v_pk_add_f32 v[174:175], v[174:175], s[44:45] op_sel_hi:[1,0]
	v_rcp_f32_e32 v172, v172
	v_rcp_f32_e32 v173, v173
	v_rcp_f32_e32 v174, v174
	v_rcp_f32_e32 v175, v175
	s_mov_b32 s26, 0x16000
	v_lshl_add_u64 v[170:171], v[186:187], 0, s[26:27]
	v_pk_mul_f32 v[176:177], v[176:177], v[172:173]
	v_pk_mul_f32 v[178:179], v[178:179], v[174:175]
	v_cvt_pk_bf16_f32 v176, v176, v177
	v_cvt_pk_bf16_f32 v177, v178, v179
	global_store_dwordx2 v[170:171], v[176:177], off offset:8
	v_pk_mul_f32 v[172:173], v[56:57], s[40:41] op_sel_hi:[1,0]
	v_pk_mul_f32 v[174:175], v[58:59], s[40:41] op_sel_hi:[1,0]
	v_pk_mul_f32 v[172:173], v[56:57], v[172:173]
	v_pk_mul_f32 v[174:175], v[58:59], v[174:175]
	v_pk_fma_f32 v[172:173], v[56:57], v[172:173], v[56:57]
	v_pk_fma_f32 v[174:175], v[58:59], v[174:175], v[58:59]
	v_pk_mul_f32 v[172:173], v[172:173], s[42:43] op_sel_hi:[1,0]
	v_pk_mul_f32 v[174:175], v[174:175], s[42:43] op_sel_hi:[1,0]
	v_pk_mul_f32 v[176:177], v[60:61], v[56:57]
	v_pk_mul_f32 v[178:179], v[62:63], v[58:59]
	v_exp_f32_e32 v172, v172
	v_exp_f32_e32 v173, v173
	v_exp_f32_e32 v174, v174
	v_exp_f32_e32 v175, v175
	v_pk_add_f32 v[172:173], v[172:173], s[44:45] op_sel_hi:[1,0]
	v_pk_add_f32 v[174:175], v[174:175], s[44:45] op_sel_hi:[1,0]
	v_rcp_f32_e32 v172, v172
	v_rcp_f32_e32 v173, v173
	v_rcp_f32_e32 v174, v174
	v_rcp_f32_e32 v175, v175
	s_mov_b32 s26, 0x2c000
	v_lshl_add_u64 v[170:171], v[186:187], 0, s[26:27]
	v_pk_mul_f32 v[176:177], v[176:177], v[172:173]
	v_pk_mul_f32 v[178:179], v[178:179], v[174:175]
	v_cvt_pk_bf16_f32 v176, v176, v177
	v_cvt_pk_bf16_f32 v177, v178, v179
	global_store_dwordx2 v[170:171], v[176:177], off offset:8
	v_pk_mul_f32 v[172:173], v[48:49], s[40:41] op_sel_hi:[1,0]
	v_pk_mul_f32 v[174:175], v[50:51], s[40:41] op_sel_hi:[1,0]
	v_pk_mul_f32 v[172:173], v[48:49], v[172:173]
	v_pk_mul_f32 v[174:175], v[50:51], v[174:175]
	v_pk_fma_f32 v[172:173], v[48:49], v[172:173], v[48:49]
	v_pk_fma_f32 v[174:175], v[50:51], v[174:175], v[50:51]
	v_pk_mul_f32 v[172:173], v[172:173], s[42:43] op_sel_hi:[1,0]
	v_pk_mul_f32 v[174:175], v[174:175], s[42:43] op_sel_hi:[1,0]
	v_pk_mul_f32 v[176:177], v[52:53], v[48:49]
	v_pk_mul_f32 v[178:179], v[54:55], v[50:51]
	v_exp_f32_e32 v172, v172
	v_exp_f32_e32 v173, v173
	v_exp_f32_e32 v174, v174
	v_exp_f32_e32 v175, v175
	v_pk_add_f32 v[172:173], v[172:173], s[44:45] op_sel_hi:[1,0]
	v_pk_add_f32 v[174:175], v[174:175], s[44:45] op_sel_hi:[1,0]
	v_rcp_f32_e32 v172, v172
	v_rcp_f32_e32 v173, v173
	v_rcp_f32_e32 v174, v174
	v_rcp_f32_e32 v175, v175
	s_mov_b32 s26, 0x42000
	v_lshl_add_u64 v[170:171], v[186:187], 0, s[26:27]
	v_pk_mul_f32 v[176:177], v[176:177], v[172:173]
	v_pk_mul_f32 v[178:179], v[178:179], v[174:175]
	s_and_b64 exec, s[28:29], s[24:25]
	v_cvt_pk_bf16_f32 v176, v176, v177
	v_cvt_pk_bf16_f32 v177, v178, v179
	global_store_dwordx2 v[170:171], v[176:177], off offset:8
	s_mov_b64 exec, s[28:29]
	v_pk_fma_f32 v[216:217], v[28:29], v[100:101], v[108:109]
	v_pk_fma_f32 v[218:219], v[20:21], v[100:101], v[108:109]
	v_pk_fma_f32 v[220:221], v[30:31], v[102:103], v[110:111]
	v_pk_fma_f32 v[222:223], v[22:23], v[102:103], v[110:111]
	v_pk_fma_f32 v[224:225], v[24:25], v[116:117], v[124:125]
	v_pk_fma_f32 v[226:227], v[16:17], v[116:117], v[124:125]
	v_pk_fma_f32 v[228:229], v[26:27], v[118:119], v[126:127]
	v_pk_fma_f32 v[194:195], v[18:19], v[118:119], v[126:127]
	v_fmac_f32_dpp v216, v28, v96 row_shr:1 row_mask:0xf bank_mask:0xf
	v_fmac_f32_dpp v218, v20, v96 row_shr:1 row_mask:0xf bank_mask:0xf
	v_fmac_f32_dpp v220, v30, v98 row_shr:1 row_mask:0xf bank_mask:0xf
	v_fmac_f32_dpp v222, v22, v98 row_shr:1 row_mask:0xf bank_mask:0xf
	v_fmac_f32_dpp v224, v24, v112 row_shr:1 row_mask:0xf bank_mask:0xf
	v_fmac_f32_dpp v226, v16, v112 row_shr:1 row_mask:0xf bank_mask:0xf
	v_fmac_f32_dpp v228, v26, v114 row_shr:1 row_mask:0xf bank_mask:0xf
	v_fmac_f32_dpp v194, v18, v114 row_shr:1 row_mask:0xf bank_mask:0xf
	v_fmac_f32_dpp v216, v28, v104 row_shl:1 row_mask:0xf bank_mask:0xf
	v_fmac_f32_dpp v218, v20, v104 row_shl:1 row_mask:0xf bank_mask:0xf
	v_fmac_f32_dpp v220, v30, v106 row_shl:1 row_mask:0xf bank_mask:0xf
;     DI void operator()(const f32x4 (&acc)[2][2][4][2], const Unit& u, int wr, int wc, int fr_, int fq_) const {
;     ...
;                     CONV_ONE(acc, ai, 0, n, m, zv, vp, vm, vn); CONV_ONE(acc, ai, 1, n, m, zg, gp, gm, gn);
;                     zv = zv + vb; zg = zg + gb;
	v_fmac_f32_dpp v222, v22, v106 row_shl:1 row_mask:0xf bank_mask:0xf
	v_fmac_f32_dpp v224, v24, v120 row_shl:1 row_mask:0xf bank_mask:0xf
	v_fmac_f32_dpp v226, v16, v120 row_shl:1 row_mask:0xf bank_mask:0xf
	v_fmac_f32_dpp v228, v26, v122 row_shl:1 row_mask:0xf bank_mask:0xf
	v_fmac_f32_dpp v194, v18, v122 row_shl:1 row_mask:0xf bank_mask:0xf
	v_fmac_f32_dpp v216, v20, v204 row_ror:15 row_mask:0xf bank_mask:0xf
	v_fmac_f32_dpp v218, v28, v200 row_ror:1 row_mask:0xf bank_mask:0xf
	v_fmac_f32_dpp v220, v22, v206 row_ror:15 row_mask:0xf bank_mask:0xf
	v_fmac_f32_dpp v222, v30, v202 row_ror:1 row_mask:0xf bank_mask:0xf
	v_fmac_f32_dpp v224, v16, v212 row_ror:15 row_mask:0xf bank_mask:0xf
	v_fmac_f32_dpp v226, v24, v208 row_ror:1 row_mask:0xf bank_mask:0xf
	v_fmac_f32_dpp v228, v18, v214 row_ror:15 row_mask:0xf bank_mask:0xf
	v_fmac_f32_dpp v194, v26, v210 row_ror:1 row_mask:0xf bank_mask:0xf
	v_fmac_f32_dpp v217, v29, v97 row_shr:1 row_mask:0xf bank_mask:0xf
	v_fmac_f32_dpp v218, v12, v204 row_ror:15 row_mask:0xf bank_mask:0xf
	v_fmac_f32_dpp v221, v31, v99 row_shr:1 row_mask:0xf bank_mask:0xf
	v_fmac_f32_dpp v222, v14, v206 row_ror:15 row_mask:0xf bank_mask:0xf
	v_fmac_f32_dpp v225, v25, v113 row_shr:1 row_mask:0xf bank_mask:0xf
	v_fmac_f32_dpp v226, v8, v212 row_ror:15 row_mask:0xf bank_mask:0xf
	v_fmac_f32_dpp v229, v27, v115 row_shr:1 row_mask:0xf bank_mask:0xf
	v_fmac_f32_dpp v194, v10, v214 row_ror:15 row_mask:0xf bank_mask:0xf
	v_fmac_f32_dpp v217, v29, v105 row_shl:1 row_mask:0xf bank_mask:0xf
	v_fmac_f32_dpp v219, v21, v97 row_shr:1 row_mask:0xf bank_mask:0xf
	v_fmac_f32_dpp v221, v31, v107 row_shl:1 row_mask:0xf bank_mask:0xf
	v_fmac_f32_dpp v223, v23, v99 row_shr:1 row_mask:0xf bank_mask:0xf
	v_fmac_f32_dpp v225, v25, v121 row_shl:1 row_mask:0xf bank_mask:0xf
	v_fmac_f32_dpp v227, v17, v113 row_shr:1 row_mask:0xf bank_mask:0xf
	v_fmac_f32_dpp v229, v27, v123 row_shl:1 row_mask:0xf bank_mask:0xf
	v_fmac_f32_dpp v195, v19, v115 row_shr:1 row_mask:0xf bank_mask:0xf
	v_fmac_f32_dpp v217, v21, v205 row_ror:15 row_mask:0xf bank_mask:0xf
	v_fmac_f32_dpp v219, v21, v105 row_shl:1 row_mask:0xf bank_mask:0xf
	v_fmac_f32_dpp v221, v23, v207 row_ror:15 row_mask:0xf bank_mask:0xf
	v_fmac_f32_dpp v223, v23, v107 row_shl:1 row_mask:0xf bank_mask:0xf
	v_fmac_f32_dpp v225, v17, v213 row_ror:15 row_mask:0xf bank_mask:0xf
	v_fmac_f32_dpp v227, v17, v121 row_shl:1 row_mask:0xf bank_mask:0xf
	v_fmac_f32_dpp v229, v19, v215 row_ror:15 row_mask:0xf bank_mask:0xf
	v_fmac_f32_dpp v195, v19, v123 row_shl:1 row_mask:0xf bank_mask:0xf
	v_fmac_f32_dpp v219, v29, v201 row_ror:1 row_mask:0xf bank_mask:0xf
	v_fmac_f32_dpp v223, v31, v203 row_ror:1 row_mask:0xf bank_mask:0xf
	v_fmac_f32_dpp v227, v25, v209 row_ror:1 row_mask:0xf bank_mask:0xf
	v_fmac_f32_dpp v195, v27, v211 row_ror:1 row_mask:0xf bank_mask:0xf
	v_fmac_f32_dpp v219, v13, v205 row_ror:15 row_mask:0xf bank_mask:0xf
	v_fmac_f32_dpp v223, v15, v207 row_ror:15 row_mask:0xf bank_mask:0xf
	v_fmac_f32_dpp v227, v9, v213 row_ror:15 row_mask:0xf bank_mask:0xf
	v_fmac_f32_dpp v195, v11, v215 row_ror:15 row_mask:0xf bank_mask:0xf
	v_pk_fma_f32 v[28:29], v[12:13], v[100:101], v[108:109]
	v_pk_fma_f32 v[30:31], v[14:15], v[102:103], v[110:111]
	v_pk_fma_f32 v[24:25], v[8:9], v[116:117], v[124:125]
	v_pk_fma_f32 v[26:27], v[10:11], v[118:119], v[126:127]
	v_fmac_f32_dpp v28, v12, v96 row_shr:1 row_mask:0xf bank_mask:0xf
	v_fmac_f32_dpp v30, v14, v98 row_shr:1 row_mask:0xf bank_mask:0xf
	v_fmac_f32_dpp v24, v8, v112 row_shr:1 row_mask:0xf bank_mask:0xf
	v_fmac_f32_dpp v26, v10, v114 row_shr:1 row_mask:0xf bank_mask:0xf
	v_fmac_f32_dpp v28, v12, v104 row_shl:1 row_mask:0xf bank_mask:0xf
	v_fmac_f32_dpp v30, v14, v106 row_shl:1 row_mask:0xf bank_mask:0xf
	v_fmac_f32_dpp v24, v8, v120 row_shl:1 row_mask:0xf bank_mask:0xf
	v_fmac_f32_dpp v26, v10, v122 row_shl:1 row_mask:0xf bank_mask:0xf
	v_fmac_f32_dpp v28, v20, v200 row_ror:1 row_mask:0xf bank_mask:0xf
	v_fmac_f32_dpp v30, v22, v202 row_ror:1 row_mask:0xf bank_mask:0xf
	v_fmac_f32_dpp v24, v16, v208 row_ror:1 row_mask:0xf bank_mask:0xf
	v_fmac_f32_dpp v26, v18, v210 row_ror:1 row_mask:0xf bank_mask:0xf
	v_fmac_f32_dpp v28, v4, v204 row_ror:15 row_mask:0xf bank_mask:0xf
	v_fmac_f32_dpp v30, v6, v206 row_ror:15 row_mask:0xf bank_mask:0xf
	v_fmac_f32_dpp v24, v0, v212 row_ror:15 row_mask:0xf bank_mask:0xf
	v_fmac_f32_dpp v26, v2, v214 row_ror:15 row_mask:0xf bank_mask:0xf
	v_fmac_f32_dpp v29, v13, v97 row_shr:1 row_mask:0xf bank_mask:0xf
	v_fmac_f32_dpp v31, v15, v99 row_shr:1 row_mask:0xf bank_mask:0xf
	v_fmac_f32_dpp v25, v9, v113 row_shr:1 row_mask:0xf bank_mask:0xf
	v_fmac_f32_dpp v27, v11, v115 row_shr:1 row_mask:0xf bank_mask:0xf
	v_fmac_f32_dpp v29, v13, v105 row_shl:1 row_mask:0xf bank_mask:0xf
	v_fmac_f32_dpp v31, v15, v107 row_shl:1 row_mask:0xf bank_mask:0xf
	v_fmac_f32_dpp v25, v9, v121 row_shl:1 row_mask:0xf bank_mask:0xf
	v_fmac_f32_dpp v27, v11, v123 row_shl:1 row_mask:0xf bank_mask:0xf
	v_fmac_f32_dpp v29, v21, v201 row_ror:1 row_mask:0xf bank_mask:0xf
	v_fmac_f32_dpp v31, v23, v203 row_ror:1 row_mask:0xf bank_mask:0xf
	v_fmac_f32_dpp v25, v17, v209 row_ror:1 row_mask:0xf bank_mask:0xf
	v_fmac_f32_dpp v27, v19, v211 row_ror:1 row_mask:0xf bank_mask:0xf
	v_fmac_f32_dpp v29, v5, v205 row_ror:15 row_mask:0xf bank_mask:0xf
	v_fmac_f32_dpp v31, v7, v207 row_ror:15 row_mask:0xf bank_mask:0xf
	v_fmac_f32_dpp v25, v1, v213 row_ror:15 row_mask:0xf bank_mask:0xf
	v_fmac_f32_dpp v27, v3, v215 row_ror:15 row_mask:0xf bank_mask:0xf
	v_pk_fma_f32 v[20:21], v[4:5], v[100:101], v[108:109]
	v_pk_fma_f32 v[22:23], v[6:7], v[102:103], v[110:111]
; DI unsigned cvtpk(float lo, float hi) { unsigned r; asm volatile("v_cvt_pk_bf16_f32 %0, %1, %2" : "=v"(r) : "v"(lo), "v"(hi)); return r; }
;     DI void operator()(const f32x4 (&acc)[2][2][4][2], const Unit& u, int wr, int wc, int fr_, int fq_) const {
;     ...
;                 for (int m = 0; m < 4; ++m) { f32x4 zv, zg;
;                     CONV_ONE(acc, ai, 0, n, m, zv, vp, vm, vn); CONV_ONE(acc, ai, 1, n, m, zg, gp, gm, gn);
;                     zv = zv + vb; zg = zg + gb;
;                     float ov[4];
; #pragma unroll
;                     for (int e = 0; e < 4; ++e) { const float x = zg[e]; const float uu = 1.5957691216f * (x + 0.044715f * x * x * x);
;                         ov[e] = zv[e] * x * __builtin_amdgcn_rcpf(1.f + __expf(-uu)); }
;                     if (ROW_VALID(m)) { const int t = tok0 + 16 * m + fr; u32x2 w; w.x = cvtpk(ov[0], ov[1]); w.y = cvtpk(ov[2], ov[3]);
;                         *(u32x2*)(ACT + (size_t)t * FF + cv0 + 4 * n) = w; }
;                     __builtin_amdgcn_sched_barrier(0); }
	v_pk_fma_f32 v[16:17], v[0:1], v[116:117], v[124:125]
	v_pk_fma_f32 v[18:19], v[2:3], v[118:119], v[126:127]
	v_fmac_f32_dpp v20, v4, v96 row_shr:1 row_mask:0xf bank_mask:0xf
	v_fmac_f32_dpp v22, v6, v98 row_shr:1 row_mask:0xf bank_mask:0xf
	v_fmac_f32_dpp v16, v0, v112 row_shr:1 row_mask:0xf bank_mask:0xf
	v_fmac_f32_dpp v18, v2, v114 row_shr:1 row_mask:0xf bank_mask:0xf
	v_fmac_f32_dpp v20, v4, v104 row_shl:1 row_mask:0xf bank_mask:0xf
	v_fmac_f32_dpp v22, v6, v106 row_shl:1 row_mask:0xf bank_mask:0xf
	v_fmac_f32_dpp v16, v0, v120 row_shl:1 row_mask:0xf bank_mask:0xf
	v_fmac_f32_dpp v18, v2, v122 row_shl:1 row_mask:0xf bank_mask:0xf
	v_fmac_f32_dpp v20, v12, v200 row_ror:1 row_mask:0xf bank_mask:0xf
	v_fmac_f32_dpp v22, v14, v202 row_ror:1 row_mask:0xf bank_mask:0xf
	v_fmac_f32_dpp v16, v8, v208 row_ror:1 row_mask:0xf bank_mask:0xf
	v_fmac_f32_dpp v18, v10, v210 row_ror:1 row_mask:0xf bank_mask:0xf
	v_fmac_f32_dpp v21, v5, v97 row_shr:1 row_mask:0xf bank_mask:0xf
	v_fmac_f32_dpp v23, v7, v99 row_shr:1 row_mask:0xf bank_mask:0xf
	v_fmac_f32_dpp v17, v1, v113 row_shr:1 row_mask:0xf bank_mask:0xf
	v_fmac_f32_dpp v19, v3, v115 row_shr:1 row_mask:0xf bank_mask:0xf
	v_fmac_f32_dpp v21, v5, v105 row_shl:1 row_mask:0xf bank_mask:0xf
	v_fmac_f32_dpp v23, v7, v107 row_shl:1 row_mask:0xf bank_mask:0xf
	v_fmac_f32_dpp v17, v1, v121 row_shl:1 row_mask:0xf bank_mask:0xf
	v_fmac_f32_dpp v19, v3, v123 row_shl:1 row_mask:0xf bank_mask:0xf
	v_fmac_f32_dpp v21, v13, v201 row_ror:1 row_mask:0xf bank_mask:0xf
	v_fmac_f32_dpp v23, v15, v203 row_ror:1 row_mask:0xf bank_mask:0xf
	v_fmac_f32_dpp v17, v9, v209 row_ror:1 row_mask:0xf bank_mask:0xf
	v_fmac_f32_dpp v19, v11, v211 row_ror:1 row_mask:0xf bank_mask:0xf
	v_pk_mul_f32 v[172:173], v[224:225], s[40:41] op_sel_hi:[1,0]
	v_pk_mul_f32 v[174:175], v[228:229], s[40:41] op_sel_hi:[1,0]
	v_pk_mul_f32 v[172:173], v[224:225], v[172:173]
	v_pk_mul_f32 v[174:175], v[228:229], v[174:175]
	v_pk_fma_f32 v[172:173], v[224:225], v[172:173], v[224:225]
	v_pk_fma_f32 v[174:175], v[228:229], v[174:175], v[228:229]
	v_pk_mul_f32 v[172:173], v[172:173], s[42:43] op_sel_hi:[1,0]
	v_pk_mul_f32 v[174:175], v[174:175], s[42:43] op_sel_hi:[1,0]
	v_pk_mul_f32 v[176:177], v[216:217], v[224:225]
	v_pk_mul_f32 v[178:179], v[220:221], v[228:229]
	v_exp_f32_e32 v172, v172
	v_exp_f32_e32 v173, v173
	v_exp_f32_e32 v174, v174
	v_exp_f32_e32 v175, v175
	v_pk_add_f32 v[172:173], v[172:173], s[44:45] op_sel_hi:[1,0]
	v_pk_add_f32 v[174:175], v[174:175], s[44:45] op_sel_hi:[1,0]
	v_rcp_f32_e32 v172, v172
	v_rcp_f32_e32 v173, v173
	v_rcp_f32_e32 v174, v174
	v_rcp_f32_e32 v175, v175
	s_mov_b32 s26, 0xaa800
	v_lshl_add_u64 v[170:171], v[186:187], 0, s[26:27]
	v_pk_mul_f32 v[176:177], v[176:177], v[172:173]
	v_pk_mul_f32 v[178:179], v[178:179], v[174:175]
	s_and_b64 exec, s[28:29], s[14:15]
	v_cvt_pk_bf16_f32 v176, v176, v177
	v_cvt_pk_bf16_f32 v177, v178, v179
	global_store_dwordx2 v[170:171], v[176:177], off offset:8
	s_mov_b64 exec, s[28:29]
	v_pk_mul_f32 v[172:173], v[226:227], s[40:41] op_sel_hi:[1,0]
	v_pk_mul_f32 v[174:175], v[194:195], s[40:41] op_sel_hi:[1,0]
	v_pk_mul_f32 v[172:173], v[226:227], v[172:173]
	v_pk_mul_f32 v[174:175], v[194:195], v[174:175]
	v_pk_fma_f32 v[172:173], v[226:227], v[172:173], v[226:227]
	v_pk_fma_f32 v[174:175], v[194:195], v[174:175], v[194:195]
	v_pk_mul_f32 v[172:173], v[172:173], s[42:43] op_sel_hi:[1,0]
	v_pk_mul_f32 v[174:175], v[174:175], s[42:43] op_sel_hi:[1,0]
	v_pk_mul_f32 v[176:177], v[218:219], v[226:227]
	v_pk_mul_f32 v[178:179], v[222:223], v[194:195]
	v_exp_f32_e32 v172, v172
	v_exp_f32_e32 v173, v173
	v_exp_f32_e32 v174, v174
	v_exp_f32_e32 v175, v175
	v_pk_add_f32 v[172:173], v[172:173], s[44:45] op_sel_hi:[1,0]
	v_pk_add_f32 v[174:175], v[174:175], s[44:45] op_sel_hi:[1,0]
	v_rcp_f32_e32 v172, v172
	v_rcp_f32_e32 v173, v173
	v_rcp_f32_e32 v174, v174
	v_rcp_f32_e32 v175, v175
	s_mov_b32 s26, 0xc0800
	v_lshl_add_u64 v[170:171], v[186:187], 0, s[26:27]
	v_pk_mul_f32 v[176:177], v[176:177], v[172:173]
	v_pk_mul_f32 v[178:179], v[178:179], v[174:175]
	v_cvt_pk_bf16_f32 v176, v176, v177
	v_cvt_pk_bf16_f32 v177, v178, v179
	global_store_dwordx2 v[170:171], v[176:177], off offset:8
	v_pk_mul_f32 v[172:173], v[24:25], s[40:41] op_sel_hi:[1,0]
	v_pk_mul_f32 v[174:175], v[26:27], s[40:41] op_sel_hi:[1,0]
	v_pk_mul_f32 v[172:173], v[24:25], v[172:173]
	v_pk_mul_f32 v[174:175], v[26:27], v[174:175]
	v_pk_fma_f32 v[172:173], v[24:25], v[172:173], v[24:25]
	v_pk_fma_f32 v[174:175], v[26:27], v[174:175], v[26:27]
	v_pk_mul_f32 v[172:173], v[172:173], s[42:43] op_sel_hi:[1,0]
	v_pk_mul_f32 v[174:175], v[174:175], s[42:43] op_sel_hi:[1,0]
	v_pk_mul_f32 v[176:177], v[28:29], v[24:25]
	v_pk_mul_f32 v[178:179], v[30:31], v[26:27]
	v_exp_f32_e32 v172, v172
	v_exp_f32_e32 v173, v173
	v_exp_f32_e32 v174, v174
	v_exp_f32_e32 v175, v175
	v_pk_add_f32 v[172:173], v[172:173], s[44:45] op_sel_hi:[1,0]
	v_pk_add_f32 v[174:175], v[174:175], s[44:45] op_sel_hi:[1,0]
	v_rcp_f32_e32 v172, v172
	v_rcp_f32_e32 v173, v173
	v_rcp_f32_e32 v174, v174
	v_rcp_f32_e32 v175, v175
	s_mov_b32 s26, 0xd6800
	v_lshl_add_u64 v[170:171], v[186:187], 0, s[26:27]
	v_pk_mul_f32 v[176:177], v[176:177], v[172:173]
	v_pk_mul_f32 v[178:179], v[178:179], v[174:175]
	v_cvt_pk_bf16_f32 v176, v176, v177
	v_cvt_pk_bf16_f32 v177, v178, v179
	global_store_dwordx2 v[170:171], v[176:177], off offset:8
	v_pk_mul_f32 v[172:173], v[16:17], s[40:41] op_sel_hi:[1,0]
	v_pk_mul_f32 v[174:175], v[18:19], s[40:41] op_sel_hi:[1,0]
	v_pk_mul_f32 v[172:173], v[16:17], v[172:173]
	v_pk_mul_f32 v[174:175], v[18:19], v[174:175]
	v_pk_fma_f32 v[172:173], v[16:17], v[172:173], v[16:17]
	v_pk_fma_f32 v[174:175], v[18:19], v[174:175], v[18:19]
	v_pk_mul_f32 v[172:173], v[172:173], s[42:43] op_sel_hi:[1,0]
	v_pk_mul_f32 v[174:175], v[174:175], s[42:43] op_sel_hi:[1,0]
	v_pk_mul_f32 v[176:177], v[20:21], v[16:17]
	v_pk_mul_f32 v[178:179], v[22:23], v[18:19]
	v_exp_f32_e32 v172, v172
	v_exp_f32_e32 v173, v173
	v_exp_f32_e32 v174, v174
	v_exp_f32_e32 v175, v175
	v_pk_add_f32 v[172:173], v[172:173], s[44:45] op_sel_hi:[1,0]
	v_pk_add_f32 v[174:175], v[174:175], s[44:45] op_sel_hi:[1,0]
	v_rcp_f32_e32 v172, v172
	v_rcp_f32_e32 v173, v173
	v_rcp_f32_e32 v174, v174
	v_rcp_f32_e32 v175, v175
	s_mov_b32 s26, 0xec800
	v_lshl_add_u64 v[170:171], v[186:187], 0, s[26:27]
	v_pk_mul_f32 v[176:177], v[176:177], v[172:173]
	v_pk_mul_f32 v[178:179], v[178:179], v[174:175]
	s_and_b64 exec, s[28:29], s[24:25]
	v_cvt_pk_bf16_f32 v176, v176, v177
	v_cvt_pk_bf16_f32 v177, v178, v179
	global_store_dwordx2 v[170:171], v[176:177], off offset:8
	s_mov_b64 exec, s[28:29]
	s_mov_b64 exec, s[28:29]
	s_movk_i32 s65, 0x2000
	s_mov_b32 s93, 0x1c000
	s_branch .Lup_done
